# one static priority raise (s_setprio 1) inside the GEMM k-loops for the workgroup half with blockIdx>=256, reset to 0 after the loop
# speedup vs baseline: 1.0073x; 1.0073x over previous
.LBB0_249:
	s_and_b32 s2, s16, 15
	s_lshl_b32 s2, s2, 7
	v_add_u32_e32 v0, s2, v142
	v_ashrrev_i32_e32 v1, 31, v0
	v_lshlrev_b64 v[0:1], 11, v[0:1]
	v_lshl_add_u64 v[116:117], v[110:111], 0, v[0:1]
	v_add_u32_e32 v0, s2, v143
	v_ashrrev_i32_e32 v1, 31, v0
	v_lshlrev_b64 v[0:1], 11, v[0:1]
	v_lshl_add_u64 v[118:119], v[110:111], 0, v[0:1]
	v_add_u32_e32 v0, s2, v144
	v_ashrrev_i32_e32 v1, 31, v0
	v_lshlrev_b64 v[0:1], 11, v[0:1]
	v_lshl_add_u64 v[120:121], v[110:111], 0, v[0:1]
	v_add_u32_e32 v0, s2, v145
	v_ashrrev_i32_e32 v1, 31, v0
	s_lshl_b32 s2, s15, 11
	v_lshlrev_b64 v[0:1], 11, v[0:1]
	s_and_b32 s50, s2, 0x7c0000
	s_and_b32 s2, s15, 0xf80
	v_lshl_add_u64 v[122:123], v[110:111], 0, v[0:1]
	v_add_u32_e32 v0, s2, v97
	v_ashrrev_i32_e32 v1, 31, v0
	v_lshlrev_b64 v[0:1], 11, v[0:1]
	v_lshl_add_u64 v[126:127], v[114:115], 0, v[0:1]
	v_add_u32_e32 v0, s2, v146
	v_ashrrev_i32_e32 v1, 31, v0
	v_lshlrev_b64 v[0:1], 11, v[0:1]
	v_lshl_add_u64 v[128:129], v[114:115], 0, v[0:1]
	v_add_u32_e32 v0, s2, v147
	s_and_b32 s2, s17, 15
	v_readlane_b32 s3, v253, 46
	v_ashrrev_i32_e32 v1, 31, v0
	s_or_b32 s2, s2, s3
	v_lshlrev_b64 v[0:1], 11, v[0:1]
	s_lshl_b32 s3, s2, 7
	v_lshl_add_u64 v[130:131], v[114:115], 0, v[0:1]
	v_add_u32_e32 v0, s3, v96
	v_ashrrev_i32_e32 v1, 31, v0
	v_lshlrev_b64 v[0:1], 11, v[0:1]
	v_lshl_add_u64 v[12:13], v[98:99], 0, v[0:1]
	s_mov_b32 s2, 0x10000
	v_add_co_u32_e32 v4, vcc, s2, v12
	s_lshl_b32 s6, s17, 3
	s_nop 0
	v_addc_co_u32_e32 v5, vcc, 0, v13, vcc
	s_mov_b32 s2, 0x20000
	v_add_co_u32_e32 v8, vcc, s2, v12
	s_and_b32 s2, s6, 0xf80
	v_add_u32_e32 v16, s2, v96
	v_ashrrev_i32_e32 v17, 31, v16
	v_lshlrev_b64 v[16:17], 11, v[16:17]
	v_addc_co_u32_e32 v9, vcc, 0, v13, vcc
	v_lshl_add_u64 v[28:29], v[100:101], 0, v[16:17]
	global_load_dwordx4 v[0:3], v[12:13], off sc1
	global_load_dwordx4 v[16:19], v[28:29], off sc1
	v_add_co_u32_e32 v12, vcc, 0x30000, v12
	global_load_dwordx4 v[4:7], v[4:5], off sc1
	s_nop 0
	v_addc_co_u32_e32 v13, vcc, 0, v13, vcc
	v_add_co_u32_e32 v20, vcc, 0x10000, v28
	global_load_dwordx4 v[8:11], v[8:9], off sc1
	s_nop 0
	v_addc_co_u32_e32 v21, vcc, 0, v29, vcc
	v_add_co_u32_e32 v24, vcc, 0x20000, v28
	global_load_dwordx4 v[12:15], v[12:13], off sc1
	s_nop 0
	v_addc_co_u32_e32 v25, vcc, 0, v29, vcc
	v_add_co_u32_e32 v28, vcc, 0x30000, v28
	global_load_dwordx4 v[20:23], v[20:21], off sc1
	s_nop 0
	v_addc_co_u32_e32 v29, vcc, 0, v29, vcc
	global_load_dwordx4 v[24:27], v[24:25], off sc1
	v_mov_b32_e32 v40, 0
	global_load_dwordx4 v[28:31], v[28:29], off sc1
	v_lshl_add_u64 v[124:125], v[112:113], 0, s[50:51]
	s_mov_b64 s[6:7], 0
	v_mov_b32_e32 v41, v40
	v_mov_b32_e32 v42, v40
	v_mov_b32_e32 v43, v40
	v_mov_b32_e32 v68, v40
	v_mov_b32_e32 v69, v40
	v_mov_b32_e32 v70, v40
	v_mov_b32_e32 v71, v40
	v_mov_b32_e32 v72, v40
	v_mov_b32_e32 v73, v40
	v_mov_b32_e32 v74, v40
	v_mov_b32_e32 v75, v40
	v_mov_b32_e32 v76, v40
	v_mov_b32_e32 v77, v40
	v_mov_b32_e32 v78, v40
	v_mov_b32_e32 v79, v40
	v_mov_b32_e32 v36, v40
	v_mov_b32_e32 v37, v40
	v_mov_b32_e32 v38, v40
	v_mov_b32_e32 v39, v40
	v_mov_b32_e32 v44, v40
	v_mov_b32_e32 v45, v40
	v_mov_b32_e32 v46, v40
	v_mov_b32_e32 v47, v40
	v_mov_b32_e32 v48, v40
	v_mov_b32_e32 v49, v40
	v_mov_b32_e32 v50, v40
	v_mov_b32_e32 v51, v40
	v_mov_b32_e32 v52, v40
	v_mov_b32_e32 v53, v40
	v_mov_b32_e32 v54, v40
	v_mov_b32_e32 v55, v40
	v_mov_b32_e32 v56, v40
	v_mov_b32_e32 v57, v40
	v_mov_b32_e32 v58, v40
	v_mov_b32_e32 v59, v40
	v_mov_b32_e32 v60, v40
	v_mov_b32_e32 v61, v40
	v_mov_b32_e32 v62, v40
	v_mov_b32_e32 v63, v40
	v_mov_b32_e32 v64, v40
	v_mov_b32_e32 v65, v40
	v_mov_b32_e32 v66, v40
	v_mov_b32_e32 v67, v40
	v_mov_b32_e32 v32, v40
	v_mov_b32_e32 v33, v40
	v_mov_b32_e32 v34, v40
	v_mov_b32_e32 v35, v40
	v_mov_b32_e32 v84, v40
	v_mov_b32_e32 v85, v40
	v_mov_b32_e32 v86, v40
	v_mov_b32_e32 v87, v40
	v_mov_b32_e32 v88, v40
	v_mov_b32_e32 v89, v40
	v_mov_b32_e32 v90, v40
	v_mov_b32_e32 v91, v40
	v_mov_b32_e32 v92, v40
	v_mov_b32_e32 v93, v40
	v_mov_b32_e32 v94, v40
	v_mov_b32_e32 v95, v40
	v_mov_b32_e32 v80, v40
	v_mov_b32_e32 v81, v40
	v_mov_b32_e32 v82, v40
	v_mov_b32_e32 v83, v40
	v_readfirstlane_b32 s76, v116
	v_readfirstlane_b32 s77, v117
	s_sub_u32 s76, s76, 0x100000
	s_subb_u32 s77, s77, 0
	v_readfirstlane_b32 s78, v124
	v_readfirstlane_b32 s79, v125
	s_sub_u32 s78, s78, 0x100000
	s_subb_u32 s79, s79, 0
	v_subrev_u32_e32 v116, s76, v116
	v_subrev_u32_e32 v118, s76, v118
	v_subrev_u32_e32 v120, s76, v120
	v_subrev_u32_e32 v122, s76, v122
	v_subrev_u32_e32 v124, s78, v124
	v_subrev_u32_e32 v126, s78, v126
	v_subrev_u32_e32 v128, s78, v128
	v_subrev_u32_e32 v130, s78, v130
	v_readlane_b32 s84, v252, 0
	s_cmp_ge_u32 s84, 0x100
	s_cbranch_scc0 .Lgprio_2
	s_setprio 1
.Lgprio_2:
.LBB0_250:
	s_barrier
	s_waitcnt vmcnt(7)
	ds_write_b128 v148, v[0:3]
	s_waitcnt vmcnt(5)
	ds_write_b128 v148, v[4:7] offset:5120
	s_waitcnt vmcnt(4)
	ds_write_b128 v148, v[8:11] offset:10240
	s_waitcnt vmcnt(3)
	ds_write_b128 v148, v[12:15] offset:15360
	ds_write_b128 v148, v[16:19] offset:20480
	s_waitcnt vmcnt(2)
	ds_write_b128 v148, v[20:23] offset:25600
	s_waitcnt vmcnt(1)
	ds_write_b128 v148, v[24:27] offset:30720
	s_waitcnt vmcnt(0)
	ds_write_b128 v148, v[28:31] offset:35840
	s_add_u32 s80, s76, s6
	s_addc_u32 s81, s77, s7
	s_add_u32 s82, s78, s6
	s_addc_u32 s83, s79, s7
	s_waitcnt lgkmcnt(0)
	s_barrier
	global_load_dwordx4 v[0:3], v116, s[80:81] sc1
	global_load_dwordx4 v[4:7], v118, s[80:81] sc1
	global_load_dwordx4 v[8:11], v120, s[80:81] sc1
	global_load_dwordx4 v[12:15], v122, s[80:81] sc1
	global_load_dwordx4 v[16:19], v124, s[82:83] sc1
	global_load_dwordx4 v[20:23], v126, s[82:83] sc1
	global_load_dwordx4 v[24:27], v128, s[82:83] sc1
	global_load_dwordx4 v[28:31], v130, s[82:83] sc1
	ds_read_b128 v[150:153], v149 offset:20480
	ds_read_b128 v[158:161], v149 offset:23040
	ds_read_b128 v[162:165], v149 offset:25600
	ds_read_b128 v[166:169], v149 offset:28160
	ds_read_b128 v[154:157], v134
	ds_read_b128 v[170:173], v134 offset:2560
	ds_read_b128 v[174:177], v134 offset:5120
	ds_read_b128 v[178:181], v134 offset:7680
	ds_read_b128 v[182:185], v149 offset:20544
	ds_read_b128 v[186:189], v149 offset:23104
	ds_read_b128 v[202:205], v149 offset:25664
	ds_read_b128 v[206:209], v149 offset:28224
	s_add_u32 s6, s6, 0x80
	s_addc_u32 s7, s7, 0
	s_waitcnt lgkmcnt(7)
	v_mfma_f32_16x16x32_bf16 v[32:35], v[150:153], v[154:157], v[32:35]
	v_mfma_f32_16x16x32_bf16 v[64:67], v[158:161], v[154:157], v[64:67]
	v_mfma_f32_16x16x32_bf16 v[60:63], v[162:165], v[154:157], v[60:63]
	v_mfma_f32_16x16x32_bf16 v[56:59], v[166:169], v[154:157], v[56:59]
	ds_read_b128 v[154:157], v134 offset:64
	s_waitcnt lgkmcnt(7)
	v_mfma_f32_16x16x32_bf16 v[52:55], v[150:153], v[170:173], v[52:55]
	v_mfma_f32_16x16x32_bf16 v[48:51], v[158:161], v[170:173], v[48:51]
	v_mfma_f32_16x16x32_bf16 v[44:47], v[162:165], v[170:173], v[44:47]
	v_mfma_f32_16x16x32_bf16 v[36:39], v[166:169], v[170:173], v[36:39]
	ds_read_b128 v[170:173], v134 offset:2624
	s_waitcnt lgkmcnt(7)
	v_mfma_f32_16x16x32_bf16 v[76:79], v[150:153], v[174:177], v[76:79]
	v_mfma_f32_16x16x32_bf16 v[72:75], v[158:161], v[174:177], v[72:75]
	v_mfma_f32_16x16x32_bf16 v[68:71], v[162:165], v[174:177], v[68:71]
	v_mfma_f32_16x16x32_bf16 v[40:43], v[166:169], v[174:177], v[40:43]
	ds_read_b128 v[174:177], v134 offset:5184
	s_waitcnt lgkmcnt(7)
	v_mfma_f32_16x16x32_bf16 v[84:87], v[150:153], v[178:181], v[84:87]
	v_mfma_f32_16x16x32_bf16 v[88:91], v[158:161], v[178:181], v[88:91]
	v_mfma_f32_16x16x32_bf16 v[92:95], v[162:165], v[178:181], v[92:95]
	v_mfma_f32_16x16x32_bf16 v[80:83], v[166:169], v[178:181], v[80:83]
	ds_read_b128 v[178:181], v134 offset:7744
	s_waitcnt lgkmcnt(3)
	v_mfma_f32_16x16x32_bf16 v[32:35], v[182:185], v[154:157], v[32:35]
	v_mfma_f32_16x16x32_bf16 v[64:67], v[186:189], v[154:157], v[64:67]
	v_mfma_f32_16x16x32_bf16 v[60:63], v[202:205], v[154:157], v[60:63]
	v_mfma_f32_16x16x32_bf16 v[56:59], v[206:209], v[154:157], v[56:59]
	s_waitcnt lgkmcnt(2)
	v_mfma_f32_16x16x32_bf16 v[52:55], v[182:185], v[170:173], v[52:55]
	v_mfma_f32_16x16x32_bf16 v[48:51], v[186:189], v[170:173], v[48:51]
	v_mfma_f32_16x16x32_bf16 v[44:47], v[202:205], v[170:173], v[44:47]
	v_mfma_f32_16x16x32_bf16 v[36:39], v[206:209], v[170:173], v[36:39]
	s_waitcnt lgkmcnt(1)
	v_mfma_f32_16x16x32_bf16 v[76:79], v[182:185], v[174:177], v[76:79]
	v_mfma_f32_16x16x32_bf16 v[72:75], v[186:189], v[174:177], v[72:75]
	v_mfma_f32_16x16x32_bf16 v[68:71], v[202:205], v[174:177], v[68:71]
	v_mfma_f32_16x16x32_bf16 v[40:43], v[206:209], v[174:177], v[40:43]
	s_waitcnt lgkmcnt(0)
	v_mfma_f32_16x16x32_bf16 v[84:87], v[182:185], v[178:181], v[84:87]
	v_mfma_f32_16x16x32_bf16 v[88:91], v[186:189], v[178:181], v[88:91]
	v_mfma_f32_16x16x32_bf16 v[92:95], v[202:205], v[178:181], v[92:95]
	v_mfma_f32_16x16x32_bf16 v[80:83], v[206:209], v[178:181], v[80:83]
	s_cmpk_eq_i32 s6, 0x780
	s_cbranch_scc0 .LBB0_250
	s_setprio 0
	s_barrier
	s_waitcnt vmcnt(7)
	ds_write_b128 v148, v[0:3]
	s_waitcnt vmcnt(6)
	ds_write_b128 v148, v[4:7] offset:5120
	s_waitcnt vmcnt(5)
	ds_write_b128 v148, v[8:11] offset:10240
	s_waitcnt vmcnt(4)
	ds_write_b128 v148, v[12:15] offset:15360
	s_waitcnt vmcnt(3)
	ds_write_b128 v148, v[16:19] offset:20480
	s_waitcnt vmcnt(2)
	ds_write_b128 v148, v[20:23] offset:25600
	s_waitcnt vmcnt(1)
	ds_write_b128 v148, v[24:27] offset:30720
	s_waitcnt vmcnt(0)
	ds_write_b128 v148, v[28:31] offset:35840
	s_waitcnt lgkmcnt(0)
	s_barrier
	ds_read_b128 v[0:3], v149 offset:20480
	ds_read_b128 v[4:7], v134
	ds_read_b128 v[12:15], v149 offset:23040
	ds_read_b128 v[20:23], v149 offset:25600
	ds_read_b128 v[28:31], v149 offset:28160
	s_cmpk_lt_u32 s2, 0x800
	s_waitcnt lgkmcnt(3)
	v_mfma_f32_16x16x32_bf16 v[8:11], v[0:3], v[4:7], v[32:35]
	s_cselect_b64 s[6:7], -1, 0
	ds_read_b128 v[128:131], v149 offset:28224
	s_waitcnt lgkmcnt(3)
	v_mfma_f32_16x16x32_bf16 v[16:19], v[12:15], v[4:7], v[64:67]
	s_waitcnt lgkmcnt(2)
	v_mfma_f32_16x16x32_bf16 v[24:27], v[20:23], v[4:7], v[60:63]
	s_waitcnt lgkmcnt(1)
	v_mfma_f32_16x16x32_bf16 v[32:35], v[28:31], v[4:7], v[56:59]
	ds_read_b128 v[4:7], v134 offset:2560
	s_waitcnt lgkmcnt(0)
	v_mfma_f32_16x16x32_bf16 v[64:67], v[0:3], v[4:7], v[52:55]
	v_mfma_f32_16x16x32_bf16 v[116:119], v[12:15], v[4:7], v[48:51]
	v_mfma_f32_16x16x32_bf16 v[120:123], v[20:23], v[4:7], v[44:47]
	v_mfma_f32_16x16x32_bf16 v[36:39], v[28:31], v[4:7], v[36:39]
	ds_read_b128 v[4:7], v134 offset:5120
	s_waitcnt lgkmcnt(0)
	v_mfma_f32_16x16x32_bf16 v[124:127], v[28:31], v[4:7], v[40:43]
	s_nop 2
	ds_read_b128 v[40:43], v134 offset:7680
	v_mfma_f32_16x16x32_bf16 v[76:79], v[0:3], v[4:7], v[76:79]
	v_mfma_f32_16x16x32_bf16 v[72:75], v[12:15], v[4:7], v[72:75]
	v_mfma_f32_16x16x32_bf16 v[68:71], v[20:23], v[4:7], v[68:71]
	s_waitcnt lgkmcnt(0)
	v_mfma_f32_16x16x32_bf16 v[4:7], v[12:15], v[40:43], v[88:91]
	ds_read_b128 v[12:15], v149 offset:20544
	v_mfma_f32_16x16x32_bf16 v[84:87], v[0:3], v[40:43], v[84:87]
	s_nop 0
	ds_read_b128 v[88:91], v149 offset:23104
	v_mfma_f32_16x16x32_bf16 v[0:3], v[20:23], v[40:43], v[92:95]
	ds_read_b128 v[20:23], v134 offset:64
	s_nop 1
	ds_read_b128 v[92:95], v149 offset:25664
	s_waitcnt lgkmcnt(1)
	v_mfma_f32_16x16x32_bf16 v[56:59], v[12:15], v[20:23], v[8:11]
	s_nop 2
	ds_read_b128 v[8:11], v134 offset:2624
	v_mfma_f32_16x16x32_bf16 v[80:83], v[28:31], v[40:43], v[80:83]
	v_mfma_f32_16x16x32_bf16 v[48:51], v[128:131], v[20:23], v[32:35]
	s_waitcnt lgkmcnt(0)
	v_mfma_f32_16x16x32_bf16 v[40:43], v[12:15], v[8:11], v[64:67]
	v_mfma_f32_16x16x32_bf16 v[44:47], v[88:91], v[8:11], v[116:119]
	s_nop 1
	v_add_u32_e32 v64, s3, v133
	v_mfma_f32_16x16x32_bf16 v[32:35], v[92:95], v[8:11], v[120:123]
	v_mfma_f32_16x16x32_bf16 v[36:39], v[128:131], v[8:11], v[36:39]
	ds_read_b128 v[8:11], v134 offset:5184
	v_mfma_f32_16x16x32_bf16 v[52:55], v[92:95], v[20:23], v[24:27]
	s_waitcnt lgkmcnt(0)
	v_mfma_f32_16x16x32_bf16 v[24:27], v[12:15], v[8:11], v[76:79]
	v_mfma_f32_16x16x32_bf16 v[28:31], v[88:91], v[8:11], v[72:75]
	s_nop 2
	ds_read_b128 v[74:77], v134 offset:7744
	v_mfma_f32_16x16x32_bf16 v[60:63], v[88:91], v[20:23], v[16:19]
	v_or_b32_e32 v73, v64, v132
	v_cmp_lt_i32_e32 vcc, s22, v73
	s_and_b64 s[10:11], vcc, s[6:7]
	v_mfma_f32_16x16x32_bf16 v[16:19], v[92:95], v[8:11], v[68:71]
	v_mfma_f32_16x16x32_bf16 v[20:23], v[128:131], v[8:11], v[124:127]
	v_bfe_u32 v8, v64, 6, 6
	v_cvt_f32_ubyte0_e32 v65, v8
	v_mul_f32_e32 v66, v136, v65
	s_waitcnt lgkmcnt(0)
	v_mfma_f32_16x16x32_bf16 v[8:11], v[12:15], v[74:77], v[84:87]
	v_mul_f32_e32 v72, 0.15915494, v66
	v_mfma_f32_16x16x32_bf16 v[12:15], v[88:91], v[74:77], v[4:7]
	s_nop 2
	v_mul_f32_e32 v4, v137, v65
	v_mul_f32_e32 v5, v138, v65
	v_mul_f32_e32 v6, v139, v65
	v_mfma_f32_16x16x32_bf16 v[0:3], v[92:95], v[74:77], v[0:3]
	v_mul_f32_e32 v71, 0.15915494, v4
	v_mul_f32_e32 v70, 0.15915494, v5
	v_mul_f32_e32 v69, 0.15915494, v6
	v_mfma_f32_16x16x32_bf16 v[4:7], v[128:131], v[74:77], v[80:83]
	s_and_saveexec_b64 s[8:9], s[10:11]
	s_cbranch_execz .LBB0_253
	v_cos_f32_e32 v65, v70
	v_sin_f32_e32 v68, v70
	v_cos_f32_e32 v92, v69
	v_sin_f32_e32 v93, v69
	v_cos_f32_e32 v66, v72
	v_sin_f32_e32 v74, v72
	v_sin_f32_e32 v75, v71
	v_cos_f32_e32 v67, v71
	v_mul_f32_e32 v82, v68, v62
	v_mul_f32_e32 v86, v65, v62
	v_mov_b32_e32 v62, v59
	v_mul_f32_e32 v80, v65, v58
	v_mul_f32_e32 v84, v68, v58
	v_pk_mul_f32 v[58:59], v[92:93], v[62:63]
	v_mul_f32_e32 v90, v141, v50
	v_mul_f32_e32 v116, v140, v50
	v_mov_b32_e32 v81, v58
	v_mov_b32_e32 v83, v59
	v_mov_b32_e32 v58, v93
	v_mov_b32_e32 v59, v92
	v_mov_b32_e32 v50, v55
	v_pk_mul_f32 v[76:77], v[74:75], v[60:61]
	v_pk_mul_f32 v[60:61], v[66:67], v[60:61]
	v_pk_mul_f32 v[78:79], v[104:105], v[48:49]
	v_mul_f32_e32 v88, v140, v54
	v_mul_f32_e32 v94, v141, v54
	v_pk_mul_f32 v[58:59], v[58:59], v[62:63]
	v_pk_mul_f32 v[54:55], v[106:107], v[50:51]
	v_pk_mul_f32 v[50:51], v[108:109], v[50:51]
	v_pk_mul_f32 v[48:49], v[102:103], v[48:49]
	v_mov_b32_e32 v85, v58
	v_mov_b32_e32 v87, v59
	v_mov_b32_e32 v89, v54
	v_mov_b32_e32 v91, v55
	v_mov_b32_e32 v95, v50
	v_mov_b32_e32 v117, v51
	v_pk_fma_f32 v[66:67], v[66:67], v[56:57], v[76:77] neg_lo:[0,0,1] neg_hi:[0,0,1]
	v_pk_fma_f32 v[60:61], v[74:75], v[56:57], v[60:61]
	v_pk_fma_f32 v[74:75], v[102:103], v[52:53], v[78:79] neg_lo:[0,0,1] neg_hi:[0,0,1]
	v_pk_add_f32 v[58:59], v[80:81], v[82:83] neg_lo:[0,1] neg_hi:[0,1]
	v_pk_add_f32 v[62:63], v[84:85], v[86:87]
	v_pk_add_f32 v[54:55], v[88:89], v[90:91] neg_lo:[0,1] neg_hi:[0,1]
	v_pk_fma_f32 v[48:49], v[104:105], v[52:53], v[48:49]
	v_pk_add_f32 v[50:51], v[94:95], v[116:117]
	v_mov_b32_e32 v56, v66
	v_mov_b32_e32 v57, v67
	v_mov_b32_e32 v52, v74
	v_mov_b32_e32 v53, v75

.LBB0_296:
	s_and_b32 s2, s16, 7
	v_readlane_b32 s3, v254, 16
	s_lshl_b32 s2, s2, 8
	v_mov_b32_e32 v160, 0
	v_add_u32_e32 v0, s3, v227
	v_add_u32_e32 v0, s2, v0
	v_ashrrev_i32_e32 v1, 31, v0
	v_lshlrev_b64 v[0:1], 11, v[0:1]
	v_readlane_b32 s3, v254, 6
	v_lshl_add_u64 v[202:203], v[198:199], 0, v[0:1]
	s_mov_b64 s[6:7], 0
	v_add_u32_e32 v0, s3, v227
	v_add_u32_e32 v0, s2, v0
	v_ashrrev_i32_e32 v1, 31, v0
	v_lshlrev_b64 v[0:1], 11, v[0:1]
	v_readlane_b32 s3, v254, 7
	v_lshl_add_u64 v[204:205], v[198:199], 0, v[0:1]
	v_mov_b32_e32 v161, v160
	v_add_u32_e32 v0, s3, v227
	v_add_u32_e32 v0, s2, v0
	v_ashrrev_i32_e32 v1, 31, v0
	v_lshlrev_b64 v[0:1], 11, v[0:1]
	v_readlane_b32 s3, v254, 8
	v_lshl_add_u64 v[206:207], v[198:199], 0, v[0:1]
	v_mov_b32_e32 v162, v160
	v_add_u32_e32 v0, s3, v227
	v_add_u32_e32 v0, s2, v0
	v_ashrrev_i32_e32 v1, 31, v0
	v_lshlrev_b64 v[0:1], 11, v[0:1]
	v_readlane_b32 s3, v254, 13
	v_lshl_add_u64 v[208:209], v[198:199], 0, v[0:1]
	v_mov_b32_e32 v163, v160
	v_add_u32_e32 v0, s3, v227
	v_add_u32_e32 v0, s2, v0
	v_ashrrev_i32_e32 v1, 31, v0
	v_lshlrev_b64 v[0:1], 11, v[0:1]
	v_readlane_b32 s3, v254, 14
	v_lshl_add_u64 v[210:211], v[198:199], 0, v[0:1]
	v_mov_b32_e32 v164, v160
	v_add_u32_e32 v0, s3, v227
	v_add_u32_e32 v0, s2, v0
	v_ashrrev_i32_e32 v1, 31, v0
	v_lshlrev_b64 v[0:1], 11, v[0:1]
	v_readlane_b32 s3, v254, 15
	v_lshl_add_u64 v[212:213], v[198:199], 0, v[0:1]
	v_mov_b32_e32 v165, v160
	v_add_u32_e32 v0, s3, v227
	v_add_u32_e32 v0, s2, v0
	v_ashrrev_i32_e32 v1, 31, v0
	v_lshlrev_b64 v[0:1], 11, v[0:1]
	v_lshl_add_u64 v[214:215], v[198:199], 0, v[0:1]
	v_add_u32_e32 v0, s2, v241
	v_ashrrev_i32_e32 v1, 31, v0
	v_lshlrev_b64 v[0:1], 11, v[0:1]
	s_and_b32 s2, s15, 0xf80
	v_lshl_add_u64 v[216:217], v[198:199], 0, v[0:1]
	v_add_u32_e32 v0, s2, v227
	v_ashrrev_i32_e32 v1, 31, v0
	v_lshlrev_b64 v[0:1], 11, v[0:1]
	v_lshl_add_u64 v[218:219], v[200:201], 0, v[0:1]
	v_add_u32_e32 v0, s2, v242
	v_ashrrev_i32_e32 v1, 31, v0
	v_lshlrev_b64 v[0:1], 11, v[0:1]
	v_lshl_add_u64 v[220:221], v[200:201], 0, v[0:1]
	v_add_u32_e32 v0, s2, v243
	v_ashrrev_i32_e32 v1, 31, v0
	v_lshlrev_b64 v[0:1], 11, v[0:1]
	v_lshl_add_u64 v[222:223], v[200:201], 0, v[0:1]
	v_add_u32_e32 v0, s2, v244
	s_and_b32 s2, s17, 7
	v_ashrrev_i32_e32 v1, 31, v0
	s_or_b32 s2, s2, s33
	v_lshlrev_b64 v[0:1], 11, v[0:1]
	s_lshl_b32 s8, s2, 8
	v_lshl_add_u64 v[224:225], v[200:201], 0, v[0:1]
	v_add_u32_e32 v0, s8, v227
	v_ashrrev_i32_e32 v1, 31, v0
	v_lshlrev_b64 v[0:1], 11, v[0:1]
	v_lshl_add_u64 v[24:25], v[192:193], 0, v[0:1]
	s_mov_b32 s2, 0x10000
	v_add_co_u32_e32 v4, vcc, s2, v24
	s_mov_b32 s2, 0x20000
	s_nop 0
	v_addc_co_u32_e32 v5, vcc, 0, v25, vcc
	v_add_co_u32_e32 v8, vcc, s2, v24
	s_mov_b32 s2, 0x30000
	s_nop 0
	v_addc_co_u32_e32 v9, vcc, 0, v25, vcc
	v_add_co_u32_e32 v12, vcc, s2, v24
	s_mov_b32 s2, 0x40000
	s_nop 0
	v_addc_co_u32_e32 v13, vcc, 0, v25, vcc
	v_add_co_u32_e32 v16, vcc, s2, v24
	s_mov_b32 s2, 0x50000
	s_nop 0
	v_addc_co_u32_e32 v17, vcc, 0, v25, vcc
	s_lshl_b32 s3, s17, 4
	v_add_co_u32_e32 v20, vcc, s2, v24
	s_mov_b32 s2, 0x60000
	s_nop 0
	v_addc_co_u32_e32 v21, vcc, 0, v25, vcc
	s_and_b32 s10, s3, 0xf80
	v_add_co_u32_e32 v26, vcc, s2, v24
	v_add_u32_e32 v32, s10, v227
	s_nop 0
	v_addc_co_u32_e32 v27, vcc, 0, v25, vcc
	v_ashrrev_i32_e32 v33, 31, v32
	v_add_co_u32_e32 v28, vcc, 0x70000, v24
	v_lshlrev_b64 v[32:33], 11, v[32:33]
	s_nop 0
	v_addc_co_u32_e32 v29, vcc, 0, v25, vcc
	v_lshl_add_u64 v[40:41], v[194:195], 0, v[32:33]
	v_add_co_u32_e32 v36, vcc, 0x10000, v40
	global_load_dwordx4 v[0:3], v[24:25], off sc1
	s_nop 0
	global_load_dwordx4 v[4:7], v[4:5], off sc1
	v_addc_co_u32_e32 v37, vcc, 0, v41, vcc
	v_add_co_u32_e32 v42, vcc, 0x20000, v40
	global_load_dwordx4 v[8:11], v[8:9], off sc1
	s_nop 0
	global_load_dwordx4 v[12:15], v[12:13], off sc1
	v_addc_co_u32_e32 v43, vcc, 0, v41, vcc
	v_add_co_u32_e32 v44, vcc, 0x30000, v40
	global_load_dwordx4 v[16:19], v[16:17], off sc1
	s_nop 0
	global_load_dwordx4 v[20:23], v[20:21], off sc1
	v_addc_co_u32_e32 v45, vcc, 0, v41, vcc
	global_load_dwordx4 v[24:27], v[26:27], off sc1
	s_nop 0
	global_load_dwordx4 v[28:31], v[28:29], off sc1
	s_nop 0
	global_load_dwordx4 v[32:35], v[40:41], off sc1
	s_nop 0
	global_load_dwordx4 v[36:39], v[36:37], off sc1
	s_nop 0
	global_load_dwordx4 v[40:43], v[42:43], off sc1
	s_nop 0
	global_load_dwordx4 v[44:47], v[44:45], off sc1
	v_mov_b32_e32 v166, v160
	v_mov_b32_e32 v167, v160
	v_mov_b32_e32 v168, v160
	v_mov_b32_e32 v169, v160
	v_mov_b32_e32 v170, v160
	v_mov_b32_e32 v171, v160
	v_mov_b32_e32 v172, v160
	v_mov_b32_e32 v173, v160
	v_mov_b32_e32 v174, v160
	v_mov_b32_e32 v175, v160
	v_mov_b32_e32 v144, v160
	v_mov_b32_e32 v145, v160
	v_mov_b32_e32 v146, v160
	v_mov_b32_e32 v147, v160
	v_mov_b32_e32 v148, v160
	v_mov_b32_e32 v149, v160
	v_mov_b32_e32 v150, v160
	v_mov_b32_e32 v151, v160
	v_mov_b32_e32 v152, v160
	v_mov_b32_e32 v153, v160
	v_mov_b32_e32 v154, v160
	v_mov_b32_e32 v155, v160
	v_mov_b32_e32 v156, v160
	v_mov_b32_e32 v157, v160
	v_mov_b32_e32 v158, v160
	v_mov_b32_e32 v159, v160
	v_mov_b32_e32 v116, v160
	v_mov_b32_e32 v117, v160
	v_mov_b32_e32 v118, v160
	v_mov_b32_e32 v119, v160
	v_mov_b32_e32 v128, v160
	v_mov_b32_e32 v129, v160
	v_mov_b32_e32 v130, v160
	v_mov_b32_e32 v131, v160
	v_mov_b32_e32 v136, v160
	v_mov_b32_e32 v137, v160
	v_mov_b32_e32 v138, v160
	v_mov_b32_e32 v139, v160
	v_mov_b32_e32 v140, v160
	v_mov_b32_e32 v141, v160
	v_mov_b32_e32 v142, v160
	v_mov_b32_e32 v143, v160
	v_mov_b32_e32 v100, v160
	v_mov_b32_e32 v101, v160
	v_mov_b32_e32 v102, v160
	v_mov_b32_e32 v103, v160
	v_mov_b32_e32 v112, v160
	v_mov_b32_e32 v113, v160
	v_mov_b32_e32 v114, v160
	v_mov_b32_e32 v115, v160
	v_mov_b32_e32 v124, v160
	v_mov_b32_e32 v125, v160
	v_mov_b32_e32 v126, v160
	v_mov_b32_e32 v127, v160
	v_mov_b32_e32 v132, v160
	v_mov_b32_e32 v133, v160
	v_mov_b32_e32 v134, v160
	v_mov_b32_e32 v135, v160
	v_mov_b32_e32 v88, v160
	v_mov_b32_e32 v89, v160
	v_mov_b32_e32 v90, v160
	v_mov_b32_e32 v91, v160
	v_mov_b32_e32 v96, v160
	v_mov_b32_e32 v97, v160
	v_mov_b32_e32 v98, v160
	v_mov_b32_e32 v99, v160
	v_mov_b32_e32 v108, v160
	v_mov_b32_e32 v109, v160
	v_mov_b32_e32 v110, v160
	v_mov_b32_e32 v111, v160
	v_mov_b32_e32 v120, v160
	v_mov_b32_e32 v121, v160
	v_mov_b32_e32 v122, v160
	v_mov_b32_e32 v123, v160
	v_mov_b32_e32 v80, v160
	v_mov_b32_e32 v81, v160
	v_mov_b32_e32 v82, v160
	v_mov_b32_e32 v83, v160
	v_mov_b32_e32 v84, v160
	v_mov_b32_e32 v85, v160
	v_mov_b32_e32 v86, v160
	v_mov_b32_e32 v87, v160
	v_mov_b32_e32 v92, v160
	v_mov_b32_e32 v93, v160
	v_mov_b32_e32 v94, v160
	v_mov_b32_e32 v95, v160
	v_mov_b32_e32 v104, v160
	v_mov_b32_e32 v105, v160
	v_mov_b32_e32 v106, v160
	v_mov_b32_e32 v107, v160
	v_mov_b32_e32 v48, v160
	v_mov_b32_e32 v49, v160
	v_mov_b32_e32 v50, v160
	v_mov_b32_e32 v51, v160
	v_mov_b32_e32 v52, v160
	v_mov_b32_e32 v53, v160
	v_mov_b32_e32 v54, v160
	v_mov_b32_e32 v55, v160
	v_mov_b32_e32 v56, v160
	v_mov_b32_e32 v57, v160
	v_mov_b32_e32 v58, v160
	v_mov_b32_e32 v59, v160
	v_mov_b32_e32 v72, v160
	v_mov_b32_e32 v73, v160
	v_mov_b32_e32 v74, v160
	v_mov_b32_e32 v75, v160
	v_mov_b32_e32 v76, v160
	v_mov_b32_e32 v77, v160
	v_mov_b32_e32 v78, v160
	v_mov_b32_e32 v79, v160
	v_mov_b32_e32 v68, v160
	v_mov_b32_e32 v69, v160
	v_mov_b32_e32 v70, v160
	v_mov_b32_e32 v71, v160
	v_mov_b32_e32 v64, v160
	v_mov_b32_e32 v65, v160
	v_mov_b32_e32 v66, v160
	v_mov_b32_e32 v67, v160
	v_mov_b32_e32 v60, v160
	v_mov_b32_e32 v61, v160
	v_mov_b32_e32 v62, v160
	v_mov_b32_e32 v63, v160
	v_readfirstlane_b32 s76, v202
	v_readfirstlane_b32 s77, v203
	s_sub_u32 s76, s76, 0x100000
	s_subb_u32 s77, s77, 0
	v_readfirstlane_b32 s78, v218
	v_readfirstlane_b32 s79, v219
	s_sub_u32 s78, s78, 0x100000
	s_subb_u32 s79, s79, 0
	v_subrev_u32_e32 v202, s76, v202
	v_subrev_u32_e32 v204, s76, v204
	v_subrev_u32_e32 v206, s76, v206
	v_subrev_u32_e32 v208, s76, v208
	v_subrev_u32_e32 v210, s76, v210
	v_subrev_u32_e32 v212, s76, v212
	v_subrev_u32_e32 v214, s76, v214
	v_subrev_u32_e32 v216, s76, v216
	v_subrev_u32_e32 v218, s78, v218
	v_subrev_u32_e32 v220, s78, v220
	v_subrev_u32_e32 v222, s78, v222
	v_subrev_u32_e32 v224, s78, v224
	v_readlane_b32 s84, v252, 0
	s_cmp_ge_u32 s84, 0x100
	s_cbranch_scc0 .Lgprio_1
	s_setprio 1
.Lgprio_1:
.LBB0_297:
	s_barrier
	s_waitcnt vmcnt(11)
	ds_write_b128 v245, v[0:3]
	s_waitcnt vmcnt(10)
	ds_write_b128 v245, v[4:7] offset:5120
	s_waitcnt vmcnt(9)
	ds_write_b128 v245, v[8:11] offset:10240
	s_waitcnt vmcnt(8)
	ds_write_b128 v245, v[12:15] offset:15360
	s_waitcnt vmcnt(7)
	ds_write_b128 v245, v[16:19] offset:20480
	s_waitcnt vmcnt(6)
	ds_write_b128 v245, v[20:23] offset:25600
	s_waitcnt vmcnt(5)
	ds_write_b128 v245, v[24:27] offset:30720
	s_waitcnt vmcnt(4)
	ds_write_b128 v245, v[28:31] offset:35840
	s_waitcnt vmcnt(3)
	ds_write_b128 v245, v[32:35] offset:40960
	s_waitcnt vmcnt(2)
	ds_write_b128 v245, v[36:39] offset:46080
	s_waitcnt vmcnt(1)
	ds_write_b128 v245, v[40:43] offset:51200
	s_waitcnt vmcnt(0)
	ds_write_b128 v245, v[44:47] offset:56320
	s_add_u32 s80, s76, s6
	s_addc_u32 s81, s77, s7
	s_add_u32 s82, s78, s6
	s_addc_u32 s83, s79, s7
	s_waitcnt lgkmcnt(0)
	s_barrier
	global_load_dwordx4 v[0:3], v202, s[80:81] sc1
	global_load_dwordx4 v[4:7], v204, s[80:81] sc1
	global_load_dwordx4 v[8:11], v206, s[80:81] sc1
	global_load_dwordx4 v[12:15], v208, s[80:81] sc1
	global_load_dwordx4 v[16:19], v210, s[80:81] sc1
	global_load_dwordx4 v[20:23], v212, s[80:81] sc1
	global_load_dwordx4 v[24:27], v214, s[80:81] sc1
	global_load_dwordx4 v[28:31], v216, s[80:81] sc1
	global_load_dwordx4 v[32:35], v218, s[82:83] sc1
	global_load_dwordx4 v[36:39], v220, s[82:83] sc1
	global_load_dwordx4 v[40:43], v222, s[82:83] sc1
	global_load_dwordx4 v[44:47], v224, s[82:83] sc1
	ds_read_b128 v[176:179], v246 offset:40960
	ds_read_b128 v[184:187], v246 offset:43520
	ds_read_b128 v[188:191], v246 offset:46080
	ds_read_b128 v[230:233], v246 offset:48640
	ds_read_b128 v[180:183], v238
	ds_read_b128 v[248:251], v238 offset:2560
	s_add_u32 s6, s6, 0x80
	s_addc_u32 s7, s7, 0
	s_waitcnt lgkmcnt(1)
	v_mfma_f32_16x16x32_bf16 v[60:63], v[176:179], v[180:183], v[60:63]
	v_mfma_f32_16x16x32_bf16 v[64:67], v[184:187], v[180:183], v[64:67]
	v_mfma_f32_16x16x32_bf16 v[68:71], v[188:191], v[180:183], v[68:71]
	v_mfma_f32_16x16x32_bf16 v[76:79], v[230:233], v[180:183], v[76:79]
	ds_read_b128 v[180:183], v238 offset:5120
	s_waitcnt lgkmcnt(1)
	v_mfma_f32_16x16x32_bf16 v[72:75], v[176:179], v[248:251], v[72:75]
	v_mfma_f32_16x16x32_bf16 v[56:59], v[184:187], v[248:251], v[56:59]
	v_mfma_f32_16x16x32_bf16 v[52:55], v[188:191], v[248:251], v[52:55]
	v_mfma_f32_16x16x32_bf16 v[48:51], v[230:233], v[248:251], v[48:51]
	ds_read_b128 v[248:251], v238 offset:7680
	s_waitcnt lgkmcnt(1)
	v_mfma_f32_16x16x32_bf16 v[104:107], v[176:179], v[180:183], v[104:107]
	v_mfma_f32_16x16x32_bf16 v[92:95], v[184:187], v[180:183], v[92:95]
	v_mfma_f32_16x16x32_bf16 v[84:87], v[188:191], v[180:183], v[84:87]
	v_mfma_f32_16x16x32_bf16 v[80:83], v[230:233], v[180:183], v[80:83]
	ds_read_b128 v[180:183], v238 offset:10240
	s_waitcnt lgkmcnt(1)
	v_mfma_f32_16x16x32_bf16 v[120:123], v[176:179], v[248:251], v[120:123]
	v_mfma_f32_16x16x32_bf16 v[108:111], v[184:187], v[248:251], v[108:111]
	v_mfma_f32_16x16x32_bf16 v[96:99], v[188:191], v[248:251], v[96:99]
	v_mfma_f32_16x16x32_bf16 v[88:91], v[230:233], v[248:251], v[88:91]
	ds_read_b128 v[248:251], v238 offset:12800
	s_waitcnt lgkmcnt(1)
	v_mfma_f32_16x16x32_bf16 v[132:135], v[176:179], v[180:183], v[132:135]
	v_mfma_f32_16x16x32_bf16 v[124:127], v[184:187], v[180:183], v[124:127]
	v_mfma_f32_16x16x32_bf16 v[112:115], v[188:191], v[180:183], v[112:115]
	v_mfma_f32_16x16x32_bf16 v[100:103], v[230:233], v[180:183], v[100:103]
	ds_read_b128 v[180:183], v238 offset:15360
	s_waitcnt lgkmcnt(1)
	v_mfma_f32_16x16x32_bf16 v[140:143], v[176:179], v[248:251], v[140:143]
	v_mfma_f32_16x16x32_bf16 v[136:139], v[184:187], v[248:251], v[136:139]
	v_mfma_f32_16x16x32_bf16 v[128:131], v[188:191], v[248:251], v[128:131]
	v_mfma_f32_16x16x32_bf16 v[116:119], v[230:233], v[248:251], v[116:119]
	ds_read_b128 v[248:251], v247
	s_waitcnt lgkmcnt(1)
	v_mfma_f32_16x16x32_bf16 v[156:159], v[176:179], v[180:183], v[156:159]
	v_mfma_f32_16x16x32_bf16 v[152:155], v[184:187], v[180:183], v[152:155]
	v_mfma_f32_16x16x32_bf16 v[148:151], v[188:191], v[180:183], v[148:151]
	v_mfma_f32_16x16x32_bf16 v[144:147], v[230:233], v[180:183], v[144:147]
	ds_read_b128 v[180:183], v238 offset:64
	s_waitcnt lgkmcnt(1)
	v_mfma_f32_16x16x32_bf16 v[172:175], v[176:179], v[248:251], v[172:175]
	ds_read_b128 v[176:179], v246 offset:41024
	v_mfma_f32_16x16x32_bf16 v[168:171], v[184:187], v[248:251], v[168:171]
	ds_read_b128 v[184:187], v246 offset:43584
	v_mfma_f32_16x16x32_bf16 v[164:167], v[188:191], v[248:251], v[164:167]
	ds_read_b128 v[188:191], v246 offset:46144
	v_mfma_f32_16x16x32_bf16 v[160:163], v[230:233], v[248:251], v[160:163]
	ds_read_b128 v[230:233], v246 offset:48704
	ds_read_b128 v[248:251], v238 offset:2624
	s_waitcnt lgkmcnt(1)
	v_mfma_f32_16x16x32_bf16 v[60:63], v[176:179], v[180:183], v[60:63]
	v_mfma_f32_16x16x32_bf16 v[64:67], v[184:187], v[180:183], v[64:67]
	v_mfma_f32_16x16x32_bf16 v[68:71], v[188:191], v[180:183], v[68:71]
	v_mfma_f32_16x16x32_bf16 v[76:79], v[230:233], v[180:183], v[76:79]
	ds_read_b128 v[180:183], v238 offset:5184
	s_waitcnt lgkmcnt(1)
	v_mfma_f32_16x16x32_bf16 v[72:75], v[176:179], v[248:251], v[72:75]
	v_mfma_f32_16x16x32_bf16 v[56:59], v[184:187], v[248:251], v[56:59]
	v_mfma_f32_16x16x32_bf16 v[52:55], v[188:191], v[248:251], v[52:55]
	v_mfma_f32_16x16x32_bf16 v[48:51], v[230:233], v[248:251], v[48:51]
	ds_read_b128 v[248:251], v238 offset:7744
	s_waitcnt lgkmcnt(1)
	v_mfma_f32_16x16x32_bf16 v[104:107], v[176:179], v[180:183], v[104:107]
	v_mfma_f32_16x16x32_bf16 v[92:95], v[184:187], v[180:183], v[92:95]
	v_mfma_f32_16x16x32_bf16 v[84:87], v[188:191], v[180:183], v[84:87]
	v_mfma_f32_16x16x32_bf16 v[80:83], v[230:233], v[180:183], v[80:83]
	ds_read_b128 v[180:183], v238 offset:10304
	s_waitcnt lgkmcnt(1)
	v_mfma_f32_16x16x32_bf16 v[120:123], v[176:179], v[248:251], v[120:123]
	v_mfma_f32_16x16x32_bf16 v[108:111], v[184:187], v[248:251], v[108:111]
	v_mfma_f32_16x16x32_bf16 v[96:99], v[188:191], v[248:251], v[96:99]
	v_mfma_f32_16x16x32_bf16 v[88:91], v[230:233], v[248:251], v[88:91]
	ds_read_b128 v[248:251], v238 offset:12864
	s_waitcnt lgkmcnt(1)
	v_mfma_f32_16x16x32_bf16 v[132:135], v[176:179], v[180:183], v[132:135]
	v_mfma_f32_16x16x32_bf16 v[124:127], v[184:187], v[180:183], v[124:127]
	v_mfma_f32_16x16x32_bf16 v[112:115], v[188:191], v[180:183], v[112:115]
	v_mfma_f32_16x16x32_bf16 v[100:103], v[230:233], v[180:183], v[100:103]
	ds_read_b128 v[180:183], v238 offset:15424
	s_waitcnt lgkmcnt(1)
	v_mfma_f32_16x16x32_bf16 v[140:143], v[176:179], v[248:251], v[140:143]
	v_mfma_f32_16x16x32_bf16 v[136:139], v[184:187], v[248:251], v[136:139]
	v_mfma_f32_16x16x32_bf16 v[128:131], v[188:191], v[248:251], v[128:131]
	v_mfma_f32_16x16x32_bf16 v[116:119], v[230:233], v[248:251], v[116:119]
	ds_read_b128 v[248:251], v247 offset:64
	s_waitcnt lgkmcnt(1)
	v_mfma_f32_16x16x32_bf16 v[156:159], v[176:179], v[180:183], v[156:159]
	v_mfma_f32_16x16x32_bf16 v[152:155], v[184:187], v[180:183], v[152:155]
	v_mfma_f32_16x16x32_bf16 v[148:151], v[188:191], v[180:183], v[148:151]
	v_mfma_f32_16x16x32_bf16 v[144:147], v[230:233], v[180:183], v[144:147]
	s_waitcnt lgkmcnt(0)
	v_mfma_f32_16x16x32_bf16 v[172:175], v[176:179], v[248:251], v[172:175]
	v_mfma_f32_16x16x32_bf16 v[168:171], v[184:187], v[248:251], v[168:171]
	v_mfma_f32_16x16x32_bf16 v[164:167], v[188:191], v[248:251], v[164:167]
	v_mfma_f32_16x16x32_bf16 v[160:163], v[230:233], v[248:251], v[160:163]
	s_cmpk_eq_i32 s6, 0x780
	s_cbranch_scc0 .LBB0_297
	s_setprio 0
	s_barrier
	s_waitcnt vmcnt(11)
	ds_write_b128 v245, v[0:3]
	s_waitcnt vmcnt(10)
	ds_write_b128 v245, v[4:7] offset:5120
	s_waitcnt vmcnt(9)
	ds_write_b128 v245, v[8:11] offset:10240
	s_waitcnt vmcnt(8)
	ds_write_b128 v245, v[12:15] offset:15360
	s_waitcnt vmcnt(7)
	ds_write_b128 v245, v[16:19] offset:20480
	s_waitcnt vmcnt(6)
	ds_write_b128 v245, v[20:23] offset:25600
	s_waitcnt vmcnt(5)
	ds_write_b128 v245, v[24:27] offset:30720
	s_waitcnt vmcnt(4)
	ds_write_b128 v245, v[28:31] offset:35840
	s_waitcnt vmcnt(3)
	ds_write_b128 v245, v[32:35] offset:40960
	s_waitcnt vmcnt(2)
	ds_write_b128 v245, v[36:39] offset:46080
	s_waitcnt vmcnt(1)
	ds_write_b128 v245, v[40:43] offset:51200
	s_waitcnt vmcnt(0)
	ds_write_b128 v245, v[44:47] offset:56320
	s_waitcnt lgkmcnt(0)
	s_barrier
	ds_read_b128 v[176:179], v246 offset:40960
	ds_read_b128 v[180:183], v246 offset:43520
	ds_read_b128 v[184:187], v246 offset:46080
	ds_read_b128 v[188:191], v246 offset:48640
	ds_read_b128 v[0:3], v238 offset:2560
	ds_read_b128 v[4:7], v238 offset:5120
	ds_read_b128 v[8:11], v238
	s_add_i32 s2, s10, 0xfffffe00
	s_cmpk_lt_u32 s2, 0x400
	s_waitcnt lgkmcnt(2)
	v_mfma_f32_16x16x32_bf16 v[218:221], v[176:179], v[0:3], v[72:75]
	v_or_b32_e32 v196, s10, v240
	ds_read_b128 v[20:23], v238 offset:15360
	s_waitcnt lgkmcnt(1)
	v_mfma_f32_16x16x32_bf16 v[202:205], v[176:179], v[8:11], v[60:63]
	v_mfma_f32_16x16x32_bf16 v[206:209], v[180:183], v[8:11], v[64:67]
	v_mfma_f32_16x16x32_bf16 v[210:213], v[184:187], v[8:11], v[68:71]
	v_mfma_f32_16x16x32_bf16 v[214:217], v[188:191], v[8:11], v[76:79]
	ds_read_b128 v[8:11], v238 offset:7680
	v_mfma_f32_16x16x32_bf16 v[222:225], v[180:183], v[0:3], v[56:59]
	v_mfma_f32_16x16x32_bf16 v[248:251], v[184:187], v[0:3], v[52:55]
	v_mfma_f32_16x16x32_bf16 v[230:233], v[188:191], v[0:3], v[48:51]
	ds_read_b128 v[0:3], v238 offset:10240
	v_mfma_f32_16x16x32_bf16 v[64:67], v[176:179], v[4:7], v[104:107]
	v_mfma_f32_16x16x32_bf16 v[68:71], v[180:183], v[4:7], v[92:95]
	v_mfma_f32_16x16x32_bf16 v[72:75], v[184:187], v[4:7], v[84:87]
	v_mfma_f32_16x16x32_bf16 v[76:79], v[188:191], v[4:7], v[80:83]
	ds_read_b128 v[4:7], v238 offset:12800
	s_nop 1
	ds_read_b128 v[80:83], v247
	s_waitcnt lgkmcnt(3)
	v_mfma_f32_16x16x32_bf16 v[48:51], v[176:179], v[8:11], v[120:123]
	v_mfma_f32_16x16x32_bf16 v[52:55], v[180:183], v[8:11], v[108:111]
	v_mfma_f32_16x16x32_bf16 v[56:59], v[184:187], v[8:11], v[96:99]
	v_mfma_f32_16x16x32_bf16 v[60:63], v[188:191], v[8:11], v[88:91]
	s_waitcnt lgkmcnt(2)
	v_mfma_f32_16x16x32_bf16 v[32:35], v[176:179], v[0:3], v[132:135]
	v_mfma_f32_16x16x32_bf16 v[36:39], v[180:183], v[0:3], v[124:127]
	v_mfma_f32_16x16x32_bf16 v[40:43], v[184:187], v[0:3], v[112:115]
	v_mfma_f32_16x16x32_bf16 v[44:47], v[188:191], v[0:3], v[100:103]
	s_waitcnt lgkmcnt(1)
	v_mfma_f32_16x16x32_bf16 v[0:3], v[184:187], v[4:7], v[128:131]
	v_mfma_f32_16x16x32_bf16 v[8:11], v[176:179], v[20:23], v[156:159]
	v_mfma_f32_16x16x32_bf16 v[12:15], v[180:183], v[20:23], v[152:155]
	v_mfma_f32_16x16x32_bf16 v[16:19], v[184:187], v[20:23], v[148:151]
	v_mfma_f32_16x16x32_bf16 v[20:23], v[188:191], v[20:23], v[144:147]
	s_waitcnt lgkmcnt(0)
	v_mfma_f32_16x16x32_bf16 v[120:123], v[176:179], v[80:83], v[172:175]
	v_mfma_f32_16x16x32_bf16 v[124:127], v[180:183], v[80:83], v[168:171]
	v_mfma_f32_16x16x32_bf16 v[128:131], v[184:187], v[80:83], v[164:167]
	v_mfma_f32_16x16x32_bf16 v[132:135], v[188:191], v[80:83], v[160:163]
	ds_read_b128 v[144:147], v246 offset:41024
	ds_read_b128 v[148:151], v246 offset:43584
	ds_read_b128 v[152:155], v246 offset:46144
	ds_read_b128 v[156:159], v246 offset:48704
	ds_read_b128 v[80:83], v238 offset:2624
	ds_read_b128 v[84:87], v238 offset:5184
	ds_read_b128 v[88:91], v238 offset:64
	ds_read_b128 v[160:163], v238 offset:7744
	ds_read_b128 v[164:167], v238 offset:10304
	v_mfma_f32_16x16x32_bf16 v[24:27], v[176:179], v[4:7], v[140:143]
	ds_read_b128 v[168:171], v238 offset:12864
	v_mfma_f32_16x16x32_bf16 v[28:31], v[180:183], v[4:7], v[136:139]
	v_mfma_f32_16x16x32_bf16 v[4:7], v[188:191], v[4:7], v[116:119]
	s_waitcnt lgkmcnt(3)
	v_mfma_f32_16x16x32_bf16 v[140:143], v[144:147], v[88:91], v[202:205]
	v_mfma_f32_16x16x32_bf16 v[136:139], v[148:151], v[88:91], v[206:209]
	v_mfma_f32_16x16x32_bf16 v[116:119], v[152:155], v[88:91], v[210:213]
	v_mfma_f32_16x16x32_bf16 v[104:107], v[156:159], v[88:91], v[214:217]
	v_mfma_f32_16x16x32_bf16 v[108:111], v[144:147], v[80:83], v[218:221]
	v_mfma_f32_16x16x32_bf16 v[112:115], v[148:151], v[80:83], v[222:225]
	v_mfma_f32_16x16x32_bf16 v[96:99], v[152:155], v[80:83], v[248:251]
	v_mfma_f32_16x16x32_bf16 v[100:103], v[156:159], v[80:83], v[230:233]
	v_mfma_f32_16x16x32_bf16 v[88:91], v[144:147], v[84:87], v[64:67]
	v_mfma_f32_16x16x32_bf16 v[92:95], v[148:151], v[84:87], v[68:71]
	v_mfma_f32_16x16x32_bf16 v[80:83], v[152:155], v[84:87], v[72:75]
	v_mfma_f32_16x16x32_bf16 v[84:87], v[156:159], v[84:87], v[76:79]
	s_waitcnt lgkmcnt(2)
	v_mfma_f32_16x16x32_bf16 v[72:75], v[144:147], v[160:163], v[48:51]
	v_mfma_f32_16x16x32_bf16 v[76:79], v[148:151], v[160:163], v[52:55]
	v_mfma_f32_16x16x32_bf16 v[64:67], v[152:155], v[160:163], v[56:59]
	v_mfma_f32_16x16x32_bf16 v[68:71], v[156:159], v[160:163], v[60:63]
	ds_read_b128 v[160:163], v238 offset:15424
	s_waitcnt lgkmcnt(2)
	v_mfma_f32_16x16x32_bf16 v[56:59], v[144:147], v[164:167], v[32:35]
	v_mfma_f32_16x16x32_bf16 v[60:63], v[148:151], v[164:167], v[36:39]
	v_mfma_f32_16x16x32_bf16 v[40:43], v[152:155], v[164:167], v[40:43]
	v_mfma_f32_16x16x32_bf16 v[44:47], v[156:159], v[164:167], v[44:47]
	ds_read_b128 v[164:167], v247 offset:64
	s_waitcnt lgkmcnt(2)
	v_mfma_f32_16x16x32_bf16 v[48:51], v[144:147], v[168:171], v[24:27]
	s_waitcnt lgkmcnt(1)
	v_mfma_f32_16x16x32_bf16 v[24:27], v[144:147], v[160:163], v[8:11]
	s_waitcnt lgkmcnt(0)
	v_mfma_f32_16x16x32_bf16 v[8:11], v[144:147], v[164:167], v[120:123]
	s_nop 2
	v_add_u32_e32 v120, s8, v239
	v_mfma_f32_16x16x32_bf16 v[52:55], v[148:151], v[168:171], v[28:31]
	s_cselect_b64 s[8:9], -1, 0
	s_cmpk_lt_u32 s10, 0x400
	s_cselect_b64 s[6:7], -1, 0
	v_mfma_f32_16x16x32_bf16 v[28:31], v[148:151], v[160:163], v[12:15]
	v_mfma_f32_16x16x32_bf16 v[12:15], v[148:151], v[164:167], v[124:127]
	s_nop 2
	v_or_b32_e32 v125, v120, v226
	v_lshlrev_b32_e32 v120, 1, v120
	v_and_b32_e32 v120, 0xfffffe00, v120
	v_add_u32_e32 v124, s14, v120
	v_mov_b64_e32 v[120:121], s[44:45]
	v_mad_i64_i32 v[120:121], s[2:3], v125, s70, v[120:121]
	s_movk_i32 s2, 0x2000
	s_nop 0
	v_cmp_gt_i32_e32 vcc, s2, v125
	s_movk_i32 s2, 0x8f
	v_and_or_b32 v122, v125, s2, v124
	v_mfma_f32_16x16x32_bf16 v[32:35], v[152:155], v[168:171], v[0:3]
	v_ashrrev_i32_e32 v123, 31, v122
	v_lshlrev_b64 v[126:127], 11, v[122:123]
	v_lshlrev_b32_e32 v122, 1, v196
	v_mfma_f32_16x16x32_bf16 v[36:39], v[156:159], v[168:171], v[4:7]
	v_mov_b32_e32 v123, v197
	v_lshl_add_u64 v[122:123], v[120:121], 0, v[122:123]
	v_lshl_add_u64 v[120:121], s[88:89], 0, v[126:127]
	v_mfma_f32_16x16x32_bf16 v[16:19], v[152:155], v[160:163], v[16:19]
	s_and_b64 s[10:11], vcc, s[8:9]
	v_lshl_add_u64 v[120:121], v[196:197], 2, v[120:121]
	v_mfma_f32_16x16x32_bf16 v[20:23], v[156:159], v[160:163], v[20:23]
	v_mfma_f32_16x16x32_bf16 v[0:3], v[152:155], v[164:167], v[128:131]
	v_mfma_f32_16x16x32_bf16 v[4:7], v[156:159], v[164:167], v[132:135]
	s_nop 1
	v_cvt_pk_bf16_f32 v128, v140, v141
	v_cvt_pk_bf16_f32 v129, v142, v143
	global_store_dwordx2 v[122:123], v[128:129], off
	s_and_saveexec_b64 s[12:13], s[10:11]
	s_cbranch_execz .LBB0_300
	s_and_b64 s[2:3], s[6:7], exec
	s_mov_b32 s2, 0x3fff800
	s_cselect_b32 s50, s2, 0x5fff000
	v_lshl_add_u64 v[126:127], v[120:121], 0, s[50:51]
	global_store_dwordx4 v[126:127], v[140:143], off

.LBB0_850:
	s_and_b32 s2, s11, 7
	v_readlane_b32 s3, v254, 16
	s_lshl_b32 s2, s2, 8
	v_mov_b32_e32 v160, 0
	v_add_u32_e32 v0, s3, v239
	v_add_u32_e32 v0, s2, v0
	v_ashrrev_i32_e32 v1, 31, v0
	v_lshlrev_b64 v[0:1], 11, v[0:1]
	v_readlane_b32 s3, v254, 6
	v_lshl_add_u64 v[192:193], v[204:205], 0, v[0:1]
	s_mov_b64 s[8:9], 0
	v_add_u32_e32 v0, s3, v239
	v_add_u32_e32 v0, s2, v0
	v_ashrrev_i32_e32 v1, 31, v0
	v_lshlrev_b64 v[0:1], 11, v[0:1]
	v_readlane_b32 s3, v254, 7
	v_lshl_add_u64 v[194:195], v[204:205], 0, v[0:1]
	v_mov_b32_e32 v161, v160
	v_add_u32_e32 v0, s3, v239
	v_add_u32_e32 v0, s2, v0
	v_ashrrev_i32_e32 v1, 31, v0
	v_lshlrev_b64 v[0:1], 11, v[0:1]
	v_readlane_b32 s3, v254, 8
	v_lshl_add_u64 v[208:209], v[204:205], 0, v[0:1]
	v_mov_b32_e32 v162, v160
	v_add_u32_e32 v0, s3, v239
	v_add_u32_e32 v0, s2, v0
	v_ashrrev_i32_e32 v1, 31, v0
	v_lshlrev_b64 v[0:1], 11, v[0:1]
	v_readlane_b32 s3, v254, 13
	v_lshl_add_u64 v[210:211], v[204:205], 0, v[0:1]
	v_mov_b32_e32 v163, v160
	v_add_u32_e32 v0, s3, v239
	v_add_u32_e32 v0, s2, v0
	v_ashrrev_i32_e32 v1, 31, v0
	v_lshlrev_b64 v[0:1], 11, v[0:1]
	v_readlane_b32 s3, v254, 14
	v_lshl_add_u64 v[212:213], v[204:205], 0, v[0:1]
	v_mov_b32_e32 v164, v160
	v_add_u32_e32 v0, s3, v239
	v_add_u32_e32 v0, s2, v0
	v_ashrrev_i32_e32 v1, 31, v0
	v_lshlrev_b64 v[0:1], 11, v[0:1]
	v_readlane_b32 s3, v254, 15
	v_lshl_add_u64 v[214:215], v[204:205], 0, v[0:1]
	v_mov_b32_e32 v165, v160
	v_add_u32_e32 v0, s3, v239
	v_add_u32_e32 v0, s2, v0
	v_ashrrev_i32_e32 v1, 31, v0
	v_lshlrev_b64 v[0:1], 11, v[0:1]
	v_readlane_b32 s3, v254, 17
	v_lshl_add_u64 v[216:217], v[204:205], 0, v[0:1]
	v_mov_b32_e32 v166, v160
	v_add_u32_e32 v0, s3, v239
	v_add_u32_e32 v0, s2, v0
	v_ashrrev_i32_e32 v1, 31, v0
	v_lshlrev_b64 v[0:1], 11, v[0:1]
	s_and_b32 s2, s10, 0x1f80
	v_lshl_add_u64 v[218:219], v[204:205], 0, v[0:1]
	v_add_u32_e32 v0, s2, v239
	v_ashrrev_i32_e32 v1, 31, v0
	v_lshlrev_b64 v[0:1], 11, v[0:1]
	v_lshl_add_u64 v[220:221], v[206:207], 0, v[0:1]
	v_add_u32_e32 v0, s2, v242
	v_ashrrev_i32_e32 v1, 31, v0
	v_lshlrev_b64 v[0:1], 11, v[0:1]
	v_lshl_add_u64 v[222:223], v[206:207], 0, v[0:1]
	v_add_u32_e32 v0, s2, v243
	v_ashrrev_i32_e32 v1, 31, v0
	v_lshlrev_b64 v[0:1], 11, v[0:1]
	v_lshl_add_u64 v[224:225], v[206:207], 0, v[0:1]
	v_add_u32_e32 v0, s2, v244
	s_and_b32 s2, s12, 7
	v_ashrrev_i32_e32 v1, 31, v0
	s_or_b32 s2, s2, s33
	v_lshlrev_b64 v[0:1], 11, v[0:1]
	s_lshl_b32 s13, s2, 8
	v_lshl_add_u64 v[226:227], v[206:207], 0, v[0:1]
	v_add_u32_e32 v0, s13, v239
	v_ashrrev_i32_e32 v1, 31, v0
	v_lshlrev_b64 v[0:1], 11, v[0:1]
	v_lshl_add_u64 v[24:25], v[198:199], 0, v[0:1]
	s_mov_b32 s2, 0x10000
	v_add_co_u32_e32 v4, vcc, s2, v24
	s_mov_b32 s2, 0x20000
	s_nop 0
	v_addc_co_u32_e32 v5, vcc, 0, v25, vcc
	v_add_co_u32_e32 v8, vcc, s2, v24
	s_mov_b32 s2, 0x30000
	s_nop 0
	v_addc_co_u32_e32 v9, vcc, 0, v25, vcc
	v_add_co_u32_e32 v12, vcc, s2, v24
	s_mov_b32 s2, 0x40000
	s_nop 0
	v_addc_co_u32_e32 v13, vcc, 0, v25, vcc
	v_add_co_u32_e32 v16, vcc, s2, v24
	s_mov_b32 s2, 0x50000
	s_nop 0
	v_addc_co_u32_e32 v17, vcc, 0, v25, vcc
	s_lshl_b32 s3, s12, 4
	v_add_co_u32_e32 v20, vcc, s2, v24
	s_mov_b32 s2, 0x60000
	s_nop 0
	v_addc_co_u32_e32 v21, vcc, 0, v25, vcc
	s_and_b32 s14, s3, 0x1f80
	v_add_co_u32_e32 v26, vcc, s2, v24
	v_add_u32_e32 v32, s14, v239
	s_nop 0
	v_addc_co_u32_e32 v27, vcc, 0, v25, vcc
	v_ashrrev_i32_e32 v33, 31, v32
	v_add_co_u32_e32 v28, vcc, 0x70000, v24
	v_lshlrev_b64 v[32:33], 11, v[32:33]
	s_nop 0
	v_addc_co_u32_e32 v29, vcc, 0, v25, vcc
	v_lshl_add_u64 v[40:41], v[200:201], 0, v[32:33]
	v_add_co_u32_e32 v36, vcc, 0x10000, v40
	global_load_dwordx4 v[0:3], v[24:25], off sc1
	s_nop 0
	global_load_dwordx4 v[4:7], v[4:5], off sc1
	v_addc_co_u32_e32 v37, vcc, 0, v41, vcc
	v_add_co_u32_e32 v42, vcc, 0x20000, v40
	global_load_dwordx4 v[8:11], v[8:9], off sc1
	s_nop 0
	global_load_dwordx4 v[12:15], v[12:13], off sc1
	v_addc_co_u32_e32 v43, vcc, 0, v41, vcc
	v_add_co_u32_e32 v44, vcc, 0x30000, v40
	global_load_dwordx4 v[16:19], v[16:17], off sc1
	s_nop 0
	global_load_dwordx4 v[20:23], v[20:21], off sc1
	v_addc_co_u32_e32 v45, vcc, 0, v41, vcc
	global_load_dwordx4 v[24:27], v[26:27], off sc1
	s_nop 0
	global_load_dwordx4 v[28:31], v[28:29], off sc1
	s_nop 0
	global_load_dwordx4 v[32:35], v[40:41], off sc1
	s_nop 0
	global_load_dwordx4 v[36:39], v[36:37], off sc1
	s_nop 0
	global_load_dwordx4 v[40:43], v[42:43], off sc1
	s_nop 0
	global_load_dwordx4 v[44:47], v[44:45], off sc1
	v_mov_b32_e32 v167, v160
	v_mov_b32_e32 v168, v160
	v_mov_b32_e32 v169, v160
	v_mov_b32_e32 v170, v160
	v_mov_b32_e32 v171, v160
	v_mov_b32_e32 v172, v160
	v_mov_b32_e32 v173, v160
	v_mov_b32_e32 v174, v160
	v_mov_b32_e32 v175, v160
	v_mov_b32_e32 v144, v160
	v_mov_b32_e32 v145, v160
	v_mov_b32_e32 v146, v160
	v_mov_b32_e32 v147, v160
	v_mov_b32_e32 v148, v160
	v_mov_b32_e32 v149, v160
	v_mov_b32_e32 v150, v160
	v_mov_b32_e32 v151, v160
	v_mov_b32_e32 v152, v160
	v_mov_b32_e32 v153, v160
	v_mov_b32_e32 v154, v160
	v_mov_b32_e32 v155, v160
	v_mov_b32_e32 v156, v160
	v_mov_b32_e32 v157, v160
	v_mov_b32_e32 v158, v160
	v_mov_b32_e32 v159, v160
	v_mov_b32_e32 v116, v160
	v_mov_b32_e32 v117, v160
	v_mov_b32_e32 v118, v160
	v_mov_b32_e32 v119, v160
	v_mov_b32_e32 v128, v160
	v_mov_b32_e32 v129, v160
	v_mov_b32_e32 v130, v160
	v_mov_b32_e32 v131, v160
	v_mov_b32_e32 v136, v160
	v_mov_b32_e32 v137, v160
	v_mov_b32_e32 v138, v160
	v_mov_b32_e32 v139, v160
	v_mov_b32_e32 v140, v160
	v_mov_b32_e32 v141, v160
	v_mov_b32_e32 v142, v160
	v_mov_b32_e32 v143, v160
	v_mov_b32_e32 v100, v160
	v_mov_b32_e32 v101, v160
	v_mov_b32_e32 v102, v160
	v_mov_b32_e32 v103, v160
	v_mov_b32_e32 v112, v160
	v_mov_b32_e32 v113, v160
	v_mov_b32_e32 v114, v160
	v_mov_b32_e32 v115, v160
	v_mov_b32_e32 v124, v160
	v_mov_b32_e32 v125, v160
	v_mov_b32_e32 v126, v160
	v_mov_b32_e32 v127, v160
	v_mov_b32_e32 v132, v160
	v_mov_b32_e32 v133, v160
	v_mov_b32_e32 v134, v160
	v_mov_b32_e32 v135, v160
	v_mov_b32_e32 v76, v160
	v_mov_b32_e32 v77, v160
	v_mov_b32_e32 v78, v160
	v_mov_b32_e32 v79, v160
	v_mov_b32_e32 v96, v160
	v_mov_b32_e32 v97, v160
	v_mov_b32_e32 v98, v160
	v_mov_b32_e32 v99, v160
	v_mov_b32_e32 v108, v160
	v_mov_b32_e32 v109, v160
	v_mov_b32_e32 v110, v160
	v_mov_b32_e32 v111, v160
	v_mov_b32_e32 v120, v160
	v_mov_b32_e32 v121, v160
	v_mov_b32_e32 v122, v160
	v_mov_b32_e32 v123, v160
	v_mov_b32_e32 v60, v160
	v_mov_b32_e32 v61, v160
	v_mov_b32_e32 v62, v160
	v_mov_b32_e32 v63, v160
	v_mov_b32_e32 v68, v160
	v_mov_b32_e32 v69, v160
	v_mov_b32_e32 v70, v160
	v_mov_b32_e32 v71, v160
	v_mov_b32_e32 v92, v160
	v_mov_b32_e32 v93, v160
	v_mov_b32_e32 v94, v160
	v_mov_b32_e32 v95, v160
	v_mov_b32_e32 v104, v160
	v_mov_b32_e32 v105, v160
	v_mov_b32_e32 v106, v160
	v_mov_b32_e32 v107, v160
	v_mov_b32_e32 v52, v160
	v_mov_b32_e32 v53, v160
	v_mov_b32_e32 v54, v160
	v_mov_b32_e32 v55, v160
	v_mov_b32_e32 v56, v160
	v_mov_b32_e32 v57, v160
	v_mov_b32_e32 v58, v160
	v_mov_b32_e32 v59, v160
	v_mov_b32_e32 v64, v160
	v_mov_b32_e32 v65, v160
	v_mov_b32_e32 v66, v160
	v_mov_b32_e32 v67, v160
	v_mov_b32_e32 v84, v160
	v_mov_b32_e32 v85, v160
	v_mov_b32_e32 v86, v160
	v_mov_b32_e32 v87, v160
	v_mov_b32_e32 v88, v160
	v_mov_b32_e32 v89, v160
	v_mov_b32_e32 v90, v160
	v_mov_b32_e32 v91, v160
	v_mov_b32_e32 v80, v160
	v_mov_b32_e32 v81, v160
	v_mov_b32_e32 v82, v160
	v_mov_b32_e32 v83, v160
	v_mov_b32_e32 v72, v160
	v_mov_b32_e32 v73, v160
	v_mov_b32_e32 v74, v160
	v_mov_b32_e32 v75, v160
	v_mov_b32_e32 v48, v160
	v_mov_b32_e32 v49, v160
	v_mov_b32_e32 v50, v160
	v_mov_b32_e32 v51, v160
	v_readfirstlane_b32 s76, v192
	v_readfirstlane_b32 s77, v193
	s_sub_u32 s76, s76, 0x100000
	s_subb_u32 s77, s77, 0
	v_readfirstlane_b32 s78, v220
	v_readfirstlane_b32 s79, v221
	s_sub_u32 s78, s78, 0x100000
	s_subb_u32 s79, s79, 0
	v_subrev_u32_e32 v192, s76, v192
	v_subrev_u32_e32 v194, s76, v194
	v_subrev_u32_e32 v208, s76, v208
	v_subrev_u32_e32 v210, s76, v210
	v_subrev_u32_e32 v212, s76, v212
	v_subrev_u32_e32 v214, s76, v214
	v_subrev_u32_e32 v216, s76, v216
	v_subrev_u32_e32 v218, s76, v218
	v_subrev_u32_e32 v220, s78, v220
	v_subrev_u32_e32 v222, s78, v222
	v_subrev_u32_e32 v224, s78, v224
	v_subrev_u32_e32 v226, s78, v226
	v_readlane_b32 s84, v252, 0
	s_cmp_ge_u32 s84, 0x100
	s_cbranch_scc0 .Lgprio_0
	s_setprio 1
.Lgprio_0:
.LBB0_851:
	s_waitcnt vmcnt(63) expcnt(7) lgkmcnt(15)
	s_barrier
	s_waitcnt vmcnt(11)
	ds_write_b128 v245, v[0:3]
	s_waitcnt vmcnt(10)
	ds_write_b128 v245, v[4:7] offset:5120
	s_waitcnt vmcnt(9)
	ds_write_b128 v245, v[8:11] offset:10240
	s_waitcnt vmcnt(8)
	ds_write_b128 v245, v[12:15] offset:15360
	s_waitcnt vmcnt(7)
	ds_write_b128 v245, v[16:19] offset:20480
	s_waitcnt vmcnt(6)
	ds_write_b128 v245, v[20:23] offset:25600
	s_waitcnt vmcnt(5)
	ds_write_b128 v245, v[24:27] offset:30720
	s_waitcnt vmcnt(4)
	ds_write_b128 v245, v[28:31] offset:35840
	s_waitcnt vmcnt(3)
	ds_write_b128 v245, v[32:35] offset:40960
	s_waitcnt vmcnt(2)
	ds_write_b128 v245, v[36:39] offset:46080
	s_waitcnt vmcnt(1)
	ds_write_b128 v245, v[40:43] offset:51200
	s_waitcnt vmcnt(0)
	ds_write_b128 v245, v[44:47] offset:56320
	s_add_u32 s80, s76, s8
	s_addc_u32 s81, s77, s9
	s_add_u32 s82, s78, s8
	s_addc_u32 s83, s79, s9
	s_waitcnt lgkmcnt(0)
	s_barrier
	global_load_dwordx4 v[0:3], v192, s[80:81] sc1
	global_load_dwordx4 v[4:7], v194, s[80:81] sc1
	global_load_dwordx4 v[8:11], v208, s[80:81] sc1
	global_load_dwordx4 v[12:15], v210, s[80:81] sc1
	global_load_dwordx4 v[16:19], v212, s[80:81] sc1
	global_load_dwordx4 v[20:23], v214, s[80:81] sc1
	global_load_dwordx4 v[24:27], v216, s[80:81] sc1
	global_load_dwordx4 v[28:31], v218, s[80:81] sc1
	global_load_dwordx4 v[32:35], v220, s[82:83] sc1
	global_load_dwordx4 v[36:39], v222, s[82:83] sc1
	global_load_dwordx4 v[40:43], v224, s[82:83] sc1
	global_load_dwordx4 v[44:47], v226, s[82:83] sc1
	ds_read_b128 v[176:179], v246 offset:40960
	ds_read_b128 v[184:187], v246 offset:43520
	ds_read_b128 v[188:191], v246 offset:46080
	ds_read_b128 v[230:233], v246 offset:48640
	ds_read_b128 v[180:183], v241
	ds_read_b128 v[248:251], v241 offset:2560
	s_add_u32 s8, s8, 0x80
	s_addc_u32 s9, s9, 0
	s_waitcnt lgkmcnt(1)
	v_mfma_f32_16x16x32_bf16 v[48:51], v[176:179], v[180:183], v[48:51]
	v_mfma_f32_16x16x32_bf16 v[72:75], v[184:187], v[180:183], v[72:75]
	v_mfma_f32_16x16x32_bf16 v[80:83], v[188:191], v[180:183], v[80:83]
	v_mfma_f32_16x16x32_bf16 v[88:91], v[230:233], v[180:183], v[88:91]
	ds_read_b128 v[180:183], v241 offset:5120
	s_waitcnt lgkmcnt(1)
	v_mfma_f32_16x16x32_bf16 v[84:87], v[176:179], v[248:251], v[84:87]
	v_mfma_f32_16x16x32_bf16 v[64:67], v[184:187], v[248:251], v[64:67]
	v_mfma_f32_16x16x32_bf16 v[56:59], v[188:191], v[248:251], v[56:59]
	v_mfma_f32_16x16x32_bf16 v[52:55], v[230:233], v[248:251], v[52:55]
	ds_read_b128 v[248:251], v241 offset:7680
	s_waitcnt lgkmcnt(1)
	v_mfma_f32_16x16x32_bf16 v[104:107], v[176:179], v[180:183], v[104:107]
	v_mfma_f32_16x16x32_bf16 v[92:95], v[184:187], v[180:183], v[92:95]
	v_mfma_f32_16x16x32_bf16 v[68:71], v[188:191], v[180:183], v[68:71]
	v_mfma_f32_16x16x32_bf16 v[60:63], v[230:233], v[180:183], v[60:63]
	ds_read_b128 v[180:183], v241 offset:10240
	s_waitcnt lgkmcnt(1)
	v_mfma_f32_16x16x32_bf16 v[120:123], v[176:179], v[248:251], v[120:123]
	v_mfma_f32_16x16x32_bf16 v[108:111], v[184:187], v[248:251], v[108:111]
	v_mfma_f32_16x16x32_bf16 v[96:99], v[188:191], v[248:251], v[96:99]
	v_mfma_f32_16x16x32_bf16 v[76:79], v[230:233], v[248:251], v[76:79]
	ds_read_b128 v[248:251], v241 offset:12800
	s_waitcnt lgkmcnt(1)
	v_mfma_f32_16x16x32_bf16 v[132:135], v[176:179], v[180:183], v[132:135]
	v_mfma_f32_16x16x32_bf16 v[124:127], v[184:187], v[180:183], v[124:127]
	v_mfma_f32_16x16x32_bf16 v[112:115], v[188:191], v[180:183], v[112:115]
	v_mfma_f32_16x16x32_bf16 v[100:103], v[230:233], v[180:183], v[100:103]
	ds_read_b128 v[180:183], v241 offset:15360
	s_waitcnt lgkmcnt(1)
	v_mfma_f32_16x16x32_bf16 v[140:143], v[176:179], v[248:251], v[140:143]
	v_mfma_f32_16x16x32_bf16 v[136:139], v[184:187], v[248:251], v[136:139]
	v_mfma_f32_16x16x32_bf16 v[128:131], v[188:191], v[248:251], v[128:131]
	v_mfma_f32_16x16x32_bf16 v[116:119], v[230:233], v[248:251], v[116:119]
	ds_read_b128 v[248:251], v247
	s_waitcnt lgkmcnt(1)
	v_mfma_f32_16x16x32_bf16 v[156:159], v[176:179], v[180:183], v[156:159]
	v_mfma_f32_16x16x32_bf16 v[152:155], v[184:187], v[180:183], v[152:155]
	v_mfma_f32_16x16x32_bf16 v[148:151], v[188:191], v[180:183], v[148:151]
	v_mfma_f32_16x16x32_bf16 v[144:147], v[230:233], v[180:183], v[144:147]
	ds_read_b128 v[180:183], v241 offset:64
	s_waitcnt lgkmcnt(1)
	v_mfma_f32_16x16x32_bf16 v[172:175], v[176:179], v[248:251], v[172:175]
	ds_read_b128 v[176:179], v246 offset:41024
	v_mfma_f32_16x16x32_bf16 v[168:171], v[184:187], v[248:251], v[168:171]
	ds_read_b128 v[184:187], v246 offset:43584
	v_mfma_f32_16x16x32_bf16 v[164:167], v[188:191], v[248:251], v[164:167]
	ds_read_b128 v[188:191], v246 offset:46144
	v_mfma_f32_16x16x32_bf16 v[160:163], v[230:233], v[248:251], v[160:163]
	ds_read_b128 v[230:233], v246 offset:48704
	ds_read_b128 v[248:251], v241 offset:2624
	s_waitcnt lgkmcnt(1)
	v_mfma_f32_16x16x32_bf16 v[48:51], v[176:179], v[180:183], v[48:51]
	v_mfma_f32_16x16x32_bf16 v[72:75], v[184:187], v[180:183], v[72:75]
	v_mfma_f32_16x16x32_bf16 v[80:83], v[188:191], v[180:183], v[80:83]
	v_mfma_f32_16x16x32_bf16 v[88:91], v[230:233], v[180:183], v[88:91]
	ds_read_b128 v[180:183], v241 offset:5184
	s_waitcnt lgkmcnt(1)
	v_mfma_f32_16x16x32_bf16 v[84:87], v[176:179], v[248:251], v[84:87]
	v_mfma_f32_16x16x32_bf16 v[64:67], v[184:187], v[248:251], v[64:67]
	v_mfma_f32_16x16x32_bf16 v[56:59], v[188:191], v[248:251], v[56:59]
	v_mfma_f32_16x16x32_bf16 v[52:55], v[230:233], v[248:251], v[52:55]
	ds_read_b128 v[248:251], v241 offset:7744
	s_waitcnt lgkmcnt(1)
	v_mfma_f32_16x16x32_bf16 v[104:107], v[176:179], v[180:183], v[104:107]
	v_mfma_f32_16x16x32_bf16 v[92:95], v[184:187], v[180:183], v[92:95]
	v_mfma_f32_16x16x32_bf16 v[68:71], v[188:191], v[180:183], v[68:71]
	v_mfma_f32_16x16x32_bf16 v[60:63], v[230:233], v[180:183], v[60:63]
	ds_read_b128 v[180:183], v241 offset:10304
	s_waitcnt lgkmcnt(1)
	v_mfma_f32_16x16x32_bf16 v[120:123], v[176:179], v[248:251], v[120:123]
	v_mfma_f32_16x16x32_bf16 v[108:111], v[184:187], v[248:251], v[108:111]
	v_mfma_f32_16x16x32_bf16 v[96:99], v[188:191], v[248:251], v[96:99]
	v_mfma_f32_16x16x32_bf16 v[76:79], v[230:233], v[248:251], v[76:79]
	ds_read_b128 v[248:251], v241 offset:12864
	s_waitcnt lgkmcnt(1)
	v_mfma_f32_16x16x32_bf16 v[132:135], v[176:179], v[180:183], v[132:135]
	v_mfma_f32_16x16x32_bf16 v[124:127], v[184:187], v[180:183], v[124:127]
	v_mfma_f32_16x16x32_bf16 v[112:115], v[188:191], v[180:183], v[112:115]
	v_mfma_f32_16x16x32_bf16 v[100:103], v[230:233], v[180:183], v[100:103]
	ds_read_b128 v[180:183], v241 offset:15424
	s_waitcnt lgkmcnt(1)
	v_mfma_f32_16x16x32_bf16 v[140:143], v[176:179], v[248:251], v[140:143]
	v_mfma_f32_16x16x32_bf16 v[136:139], v[184:187], v[248:251], v[136:139]
	v_mfma_f32_16x16x32_bf16 v[128:131], v[188:191], v[248:251], v[128:131]
	v_mfma_f32_16x16x32_bf16 v[116:119], v[230:233], v[248:251], v[116:119]
	ds_read_b128 v[248:251], v247 offset:64
	s_waitcnt lgkmcnt(1)
	v_mfma_f32_16x16x32_bf16 v[156:159], v[176:179], v[180:183], v[156:159]
	v_mfma_f32_16x16x32_bf16 v[152:155], v[184:187], v[180:183], v[152:155]
	v_mfma_f32_16x16x32_bf16 v[148:151], v[188:191], v[180:183], v[148:151]
	v_mfma_f32_16x16x32_bf16 v[144:147], v[230:233], v[180:183], v[144:147]
	s_waitcnt lgkmcnt(0)
	v_mfma_f32_16x16x32_bf16 v[172:175], v[176:179], v[248:251], v[172:175]
	v_mfma_f32_16x16x32_bf16 v[168:171], v[184:187], v[248:251], v[168:171]
	v_mfma_f32_16x16x32_bf16 v[164:167], v[188:191], v[248:251], v[164:167]
	v_mfma_f32_16x16x32_bf16 v[160:163], v[230:233], v[248:251], v[160:163]
	s_cmpk_eq_i32 s8, 0x780
	s_cbranch_scc0 .LBB0_851
	s_setprio 0
	s_barrier
	s_waitcnt vmcnt(11)
	ds_write_b128 v245, v[0:3]
	s_waitcnt vmcnt(10)
	ds_write_b128 v245, v[4:7] offset:5120
	s_waitcnt vmcnt(9)
	ds_write_b128 v245, v[8:11] offset:10240
	s_waitcnt vmcnt(8)
	ds_write_b128 v245, v[12:15] offset:15360
	s_waitcnt vmcnt(7)
	ds_write_b128 v245, v[16:19] offset:20480
	s_waitcnt vmcnt(6)
	ds_write_b128 v245, v[20:23] offset:25600
	s_waitcnt vmcnt(5)
	ds_write_b128 v245, v[24:27] offset:30720
	s_waitcnt vmcnt(4)
	ds_write_b128 v245, v[28:31] offset:35840
	s_waitcnt vmcnt(3)
	ds_write_b128 v245, v[32:35] offset:40960
	s_waitcnt vmcnt(2)
	ds_write_b128 v245, v[36:39] offset:46080
	s_waitcnt vmcnt(1)
	ds_write_b128 v245, v[40:43] offset:51200
	s_waitcnt vmcnt(0)
	ds_write_b128 v245, v[44:47] offset:56320
	s_waitcnt lgkmcnt(0)
	s_barrier
	ds_read_b128 v[208:211], v246 offset:40960
	ds_read_b128 v[212:215], v246 offset:43520
	ds_read_b128 v[216:219], v246 offset:46080
	ds_read_b128 v[220:223], v246 offset:48640
	ds_read_b128 v[0:3], v241
	ds_read_b128 v[4:7], v241 offset:2560
	ds_read_b128 v[8:11], v241 offset:5120
	ds_read_b128 v[12:15], v241 offset:12800
	v_or_b32_e32 v196, s14, v238
	s_waitcnt lgkmcnt(3)
	v_mfma_f32_16x16x32_bf16 v[180:183], v[208:211], v[0:3], v[48:51]
	s_add_i32 s12, s12, s53
	s_add_i32 s11, s11, s53
	v_mfma_f32_16x16x32_bf16 v[184:187], v[212:215], v[0:3], v[72:75]
	v_mfma_f32_16x16x32_bf16 v[188:191], v[216:219], v[0:3], v[80:83]
	v_mfma_f32_16x16x32_bf16 v[192:195], v[220:223], v[0:3], v[88:91]
	ds_read_b128 v[0:3], v241 offset:7680
	s_waitcnt lgkmcnt(3)
	v_mfma_f32_16x16x32_bf16 v[80:83], v[208:211], v[4:7], v[84:87]
	v_mfma_f32_16x16x32_bf16 v[84:87], v[212:215], v[4:7], v[64:67]
	v_mfma_f32_16x16x32_bf16 v[88:91], v[216:219], v[4:7], v[56:59]
	v_mfma_f32_16x16x32_bf16 v[176:179], v[220:223], v[4:7], v[52:55]
	ds_read_b128 v[4:7], v241 offset:10240
	s_waitcnt lgkmcnt(3)
	v_mfma_f32_16x16x32_bf16 v[72:75], v[212:215], v[8:11], v[92:95]
	s_waitcnt lgkmcnt(1)
	v_mfma_f32_16x16x32_bf16 v[56:59], v[220:223], v[0:3], v[76:79]
	s_nop 0
	ds_read_b128 v[92:95], v247
	s_nop 0
	ds_read_b128 v[76:79], v241 offset:15360
	v_mfma_f32_16x16x32_bf16 v[64:67], v[208:211], v[8:11], v[104:107]
	v_mfma_f32_16x16x32_bf16 v[68:71], v[216:219], v[8:11], v[68:71]
	v_mfma_f32_16x16x32_bf16 v[60:63], v[220:223], v[8:11], v[60:63]
	v_mfma_f32_16x16x32_bf16 v[44:47], v[208:211], v[0:3], v[120:123]
	s_waitcnt lgkmcnt(2)
	v_mfma_f32_16x16x32_bf16 v[28:31], v[208:211], v[4:7], v[132:135]
	v_mfma_f32_16x16x32_bf16 v[32:35], v[212:215], v[4:7], v[124:127]
	v_mfma_f32_16x16x32_bf16 v[36:39], v[216:219], v[4:7], v[112:115]
	v_mfma_f32_16x16x32_bf16 v[40:43], v[220:223], v[4:7], v[100:103]
	v_mfma_f32_16x16x32_bf16 v[4:7], v[212:215], v[12:15], v[136:139]
	v_mfma_f32_16x16x32_bf16 v[8:11], v[216:219], v[12:15], v[128:131]
	s_waitcnt lgkmcnt(0)
	v_mfma_f32_16x16x32_bf16 v[16:19], v[208:211], v[76:79], v[156:159]
	v_mfma_f32_16x16x32_bf16 v[20:23], v[212:215], v[76:79], v[152:155]
	v_mfma_f32_16x16x32_bf16 v[24:27], v[216:219], v[76:79], v[148:151]
	v_mfma_f32_16x16x32_bf16 v[120:123], v[220:223], v[76:79], v[144:147]
	v_mfma_f32_16x16x32_bf16 v[124:127], v[208:211], v[92:95], v[172:175]
	v_mfma_f32_16x16x32_bf16 v[128:131], v[212:215], v[92:95], v[168:171]
	v_mfma_f32_16x16x32_bf16 v[132:135], v[216:219], v[92:95], v[164:167]
	v_mfma_f32_16x16x32_bf16 v[136:139], v[220:223], v[92:95], v[160:163]
	ds_read_b128 v[148:151], v246 offset:41024
	ds_read_b128 v[152:155], v246 offset:43584
	ds_read_b128 v[156:159], v246 offset:46144
	ds_read_b128 v[160:163], v246 offset:48704
	ds_read_b128 v[76:79], v241 offset:64
	ds_read_b128 v[92:95], v241 offset:2624
	ds_read_b128 v[164:167], v241 offset:5184
	ds_read_b128 v[168:171], v241 offset:7744
	ds_read_b128 v[172:175], v241 offset:10304
	v_mfma_f32_16x16x32_bf16 v[48:51], v[212:215], v[0:3], v[108:111]
	v_mfma_f32_16x16x32_bf16 v[52:55], v[216:219], v[0:3], v[96:99]
	v_mfma_f32_16x16x32_bf16 v[0:3], v[208:211], v[12:15], v[140:143]
	v_mfma_f32_16x16x32_bf16 v[12:15], v[220:223], v[12:15], v[116:119]
	s_waitcnt lgkmcnt(4)
	v_mfma_f32_16x16x32_bf16 v[144:147], v[148:151], v[76:79], v[180:183]
	v_mfma_f32_16x16x32_bf16 v[116:119], v[152:155], v[76:79], v[184:187]
	v_mfma_f32_16x16x32_bf16 v[140:143], v[156:159], v[76:79], v[188:191]
	v_mfma_f32_16x16x32_bf16 v[112:115], v[160:163], v[76:79], v[192:195]
	s_waitcnt lgkmcnt(3)
	v_mfma_f32_16x16x32_bf16 v[108:111], v[148:151], v[92:95], v[80:83]
	v_mfma_f32_16x16x32_bf16 v[100:103], v[152:155], v[92:95], v[84:87]
	v_mfma_f32_16x16x32_bf16 v[104:107], v[156:159], v[92:95], v[88:91]
	v_mfma_f32_16x16x32_bf16 v[96:99], v[160:163], v[92:95], v[176:179]
	s_waitcnt lgkmcnt(2)
	v_mfma_f32_16x16x32_bf16 v[92:95], v[148:151], v[164:167], v[64:67]
	v_mfma_f32_16x16x32_bf16 v[84:87], v[152:155], v[164:167], v[72:75]
	v_mfma_f32_16x16x32_bf16 v[88:91], v[156:159], v[164:167], v[68:71]
	v_mfma_f32_16x16x32_bf16 v[80:83], v[160:163], v[164:167], v[60:63]
	ds_read_b128 v[164:167], v241 offset:12864
	s_waitcnt lgkmcnt(2)
	v_mfma_f32_16x16x32_bf16 v[76:79], v[148:151], v[168:171], v[44:47]
	v_mfma_f32_16x16x32_bf16 v[68:71], v[152:155], v[168:171], v[48:51]
	v_mfma_f32_16x16x32_bf16 v[72:75], v[156:159], v[168:171], v[52:55]
	v_mfma_f32_16x16x32_bf16 v[64:67], v[160:163], v[168:171], v[56:59]
	ds_read_b128 v[168:171], v241 offset:15424
	s_waitcnt lgkmcnt(2)
	v_mfma_f32_16x16x32_bf16 v[60:63], v[148:151], v[172:175], v[28:31]
	s_waitcnt lgkmcnt(0)
	v_mfma_f32_16x16x32_bf16 v[28:31], v[148:151], v[168:171], v[16:19]
	v_mfma_f32_16x16x32_bf16 v[16:19], v[160:163], v[168:171], v[120:123]
	s_nop 2
	v_mul_f32_e32 v123, 0xbfb8aa3b, v144
	v_mfma_f32_16x16x32_bf16 v[52:55], v[152:155], v[172:175], v[32:35]
	v_exp_f32_e32 v123, v123
	v_add_u32_e32 v122, s13, v240
	v_lshl_add_u64 v[120:121], v[202:203], 0, v[196:197]
	v_mfma_f32_16x16x32_bf16 v[56:59], v[156:159], v[172:175], v[36:39]
	v_add_f32_e32 v123, 1.0, v123
	v_mfma_f32_16x16x32_bf16 v[48:51], v[160:163], v[172:175], v[40:43]
	ds_read_b128 v[172:175], v247 offset:64
	v_mfma_f32_16x16x32_bf16 v[32:35], v[160:163], v[164:167], v[12:15]
	s_waitcnt lgkmcnt(0)
	v_mfma_f32_16x16x32_bf16 v[12:15], v[148:151], v[172:175], v[124:127]
	s_nop 2
	v_rcp_f32_e32 v126, v123
	v_mul_f32_e32 v123, 0xbfb8aa3b, v145
	v_exp_f32_e32 v123, v123
	v_mfma_f32_16x16x32_bf16 v[36:39], v[152:155], v[164:167], v[4:7]
	v_mad_i64_i32 v[124:125], s[2:3], v122, s46, v[120:121]
	v_add_f32_e32 v123, 1.0, v123
	v_rcp_f32_e32 v127, v123
	v_mul_f32_e32 v123, 0xbfb8aa3b, v146
	v_exp_f32_e32 v123, v123
	v_mfma_f32_16x16x32_bf16 v[4:7], v[152:155], v[172:175], v[128:131]
	v_mul_f32_e64 v126, v144, v126
	v_mul_f32_e64 v127, v145, v127
	v_add_f32_e32 v123, 1.0, v123
	v_rcp_f32_e32 v128, v123
	v_mul_f32_e32 v123, 0xbfb8aa3b, v147
	v_exp_f32_e32 v123, v123
	v_pk_mul_f32 v[126:127], v[140:141], v[126:127]
	v_mfma_f32_16x16x32_bf16 v[44:47], v[148:151], v[164:167], v[0:3]
	v_cvt_pk_bf16_f32 v126, v126, v127
	v_add_f32_e32 v123, 1.0, v123
	v_rcp_f32_e32 v129, v123
	v_mul_f32_e32 v123, 0xbfb8aa3b, v116
	v_exp_f32_e32 v123, v123
	v_mfma_f32_16x16x32_bf16 v[40:43], v[156:159], v[164:167], v[8:11]
	v_mul_f32_e64 v128, v146, v128
	v_mul_f32_e64 v129, v147, v129
	v_add_f32_e32 v123, 1.0, v123
	v_pk_mul_f32 v[128:129], v[142:143], v[128:129]
	v_mfma_f32_16x16x32_bf16 v[24:27], v[156:159], v[168:171], v[24:27]
	v_cvt_pk_bf16_f32 v127, v128, v129
	global_store_dwordx2 v[124:125], v[126:127], off
	v_rcp_f32_e32 v126, v123
	v_mul_f32_e32 v123, 0xbfb8aa3b, v117
	v_exp_f32_e32 v123, v123
	v_mfma_f32_16x16x32_bf16 v[20:23], v[152:155], v[168:171], v[20:23]
	v_add_f32_e32 v123, 1.0, v123
	v_rcp_f32_e32 v127, v123
	v_mfma_f32_16x16x32_bf16 v[8:11], v[156:159], v[172:175], v[132:135]
	v_mul_f32_e64 v116, v116, v126
	v_mul_f32_e64 v117, v117, v127
	v_pk_mul_f32 v[112:113], v[112:113], v[116:117]
	v_mfma_f32_16x16x32_bf16 v[0:3], v[160:163], v[172:175], v[136:139]
	v_cvt_pk_bf16_f32 v112, v112, v113
	v_mul_f32_e32 v113, 0xbfb8aa3b, v118
	v_exp_f32_e32 v113, v113
	s_nop 0
	v_add_f32_e32 v113, 1.0, v113
	v_rcp_f32_e32 v116, v113
	v_mul_f32_e32 v113, 0xbfb8aa3b, v119
	v_exp_f32_e32 v113, v113
	s_nop 0
	v_add_f32_e32 v113, 1.0, v113
	v_rcp_f32_e32 v117, v113
	s_nop 0
	v_pk_mul_f32 v[116:117], v[118:119], v[116:117]
	s_nop 0
	v_pk_mul_f32 v[114:115], v[114:115], v[116:117]
	s_nop 0
	v_cvt_pk_bf16_f32 v113, v114, v115
	v_mul_f32_e32 v114, 0xbfb8aa3b, v108
	v_mul_f32_e32 v115, 0xbfb8aa3b, v109
	v_exp_f32_e32 v114, v114
	v_exp_f32_e32 v115, v115
	global_store_dwordx2 v[124:125], v[112:113], off offset:32
	v_or_b32_e32 v112, 16, v122
	v_add_f32_e32 v114, 1.0, v114
	v_add_f32_e32 v115, 1.0, v115
	v_rcp_f32_e32 v114, v114
	v_rcp_f32_e32 v115, v115
	v_mad_i64_i32 v[112:113], s[2:3], v112, s46, v[120:121]
	v_pk_mul_f32 v[108:109], v[108:109], v[114:115]
	s_nop 0
	v_pk_mul_f32 v[104:105], v[104:105], v[108:109]
	s_nop 0
	v_cvt_pk_bf16_f32 v104, v104, v105
	v_mul_f32_e32 v105, 0xbfb8aa3b, v110
	v_exp_f32_e32 v105, v105
	s_nop 0
	v_add_f32_e32 v105, 1.0, v105
	v_rcp_f32_e32 v108, v105
	v_mul_f32_e32 v105, 0xbfb8aa3b, v111
	v_exp_f32_e32 v105, v105
	s_nop 0
	v_add_f32_e32 v105, 1.0, v105
	v_rcp_f32_e32 v109, v105
	s_nop 0
	v_pk_mul_f32 v[108:109], v[110:111], v[108:109]
	s_nop 0
	v_pk_mul_f32 v[106:107], v[106:107], v[108:109]
	s_nop 0
	v_cvt_pk_bf16_f32 v105, v106, v107
	global_store_dwordx2 v[112:113], v[104:105], off
	v_mul_f32_e32 v104, 0xbfb8aa3b, v100
	v_mul_f32_e32 v105, 0xbfb8aa3b, v101
	v_exp_f32_e32 v104, v104
	v_exp_f32_e32 v105, v105
	v_add_f32_e32 v104, 1.0, v104
	v_add_f32_e32 v105, 1.0, v105
	v_rcp_f32_e32 v104, v104
	v_rcp_f32_e32 v105, v105
	s_nop 0
	v_pk_mul_f32 v[100:101], v[100:101], v[104:105]
	s_nop 0
	v_pk_mul_f32 v[96:97], v[96:97], v[100:101]
	s_nop 0
	v_cvt_pk_bf16_f32 v96, v96, v97
	v_mul_f32_e32 v97, 0xbfb8aa3b, v102
	v_exp_f32_e32 v97, v97
	s_nop 0
	v_add_f32_e32 v97, 1.0, v97
	v_rcp_f32_e32 v100, v97
	v_mul_f32_e32 v97, 0xbfb8aa3b, v103
	v_exp_f32_e32 v97, v97
	s_nop 0
	v_add_f32_e32 v97, 1.0, v97
	v_rcp_f32_e32 v101, v97
	s_nop 0
	v_pk_mul_f32 v[100:101], v[102:103], v[100:101]
	s_nop 0
	v_pk_mul_f32 v[98:99], v[98:99], v[100:101]
	s_nop 0
	v_cvt_pk_bf16_f32 v97, v98, v99
	v_mul_f32_e32 v98, 0xbfb8aa3b, v92
	v_mul_f32_e32 v99, 0xbfb8aa3b, v93
	v_exp_f32_e32 v98, v98
	v_exp_f32_e32 v99, v99
	global_store_dwordx2 v[112:113], v[96:97], off offset:32
	v_or_b32_e32 v96, 32, v122
	v_add_f32_e32 v98, 1.0, v98
	v_add_f32_e32 v99, 1.0, v99
	v_rcp_f32_e32 v98, v98
	v_rcp_f32_e32 v99, v99
	v_mad_i64_i32 v[96:97], s[2:3], v96, s46, v[120:121]
	v_pk_mul_f32 v[92:93], v[92:93], v[98:99]
	s_nop 0
	v_pk_mul_f32 v[88:89], v[88:89], v[92:93]
	s_nop 0
	v_cvt_pk_bf16_f32 v88, v88, v89
	v_mul_f32_e32 v89, 0xbfb8aa3b, v94
	v_exp_f32_e32 v89, v89
	s_nop 0
	v_add_f32_e32 v89, 1.0, v89
	v_rcp_f32_e32 v92, v89
	v_mul_f32_e32 v89, 0xbfb8aa3b, v95
	v_exp_f32_e32 v89, v89
	s_nop 0
	v_add_f32_e32 v89, 1.0, v89
	v_rcp_f32_e32 v93, v89
	s_nop 0
	v_pk_mul_f32 v[92:93], v[94:95], v[92:93]
	s_nop 0
	v_pk_mul_f32 v[90:91], v[90:91], v[92:93]
	s_nop 0
	v_cvt_pk_bf16_f32 v89, v90, v91
	global_store_dwordx2 v[96:97], v[88:89], off
	v_mul_f32_e32 v88, 0xbfb8aa3b, v84
	v_mul_f32_e32 v89, 0xbfb8aa3b, v85
	v_exp_f32_e32 v88, v88
	v_exp_f32_e32 v89, v89
	v_add_f32_e32 v88, 1.0, v88
	v_add_f32_e32 v89, 1.0, v89
	v_rcp_f32_e32 v88, v88
	v_rcp_f32_e32 v89, v89
	s_nop 0
	v_pk_mul_f32 v[84:85], v[84:85], v[88:89]
	s_nop 0
	v_pk_mul_f32 v[80:81], v[80:81], v[84:85]
	s_nop 0
	v_cvt_pk_bf16_f32 v80, v80, v81
	v_mul_f32_e32 v81, 0xbfb8aa3b, v86
	v_exp_f32_e32 v81, v81
	s_nop 0
	v_add_f32_e32 v81, 1.0, v81
	v_rcp_f32_e32 v84, v81
	v_mul_f32_e32 v81, 0xbfb8aa3b, v87
	v_exp_f32_e32 v81, v81
	s_nop 0
	v_add_f32_e32 v81, 1.0, v81
	v_rcp_f32_e32 v85, v81
	s_nop 0
	v_pk_mul_f32 v[84:85], v[86:87], v[84:85]
	s_nop 0
	v_pk_mul_f32 v[82:83], v[82:83], v[84:85]
	s_nop 0
	v_cvt_pk_bf16_f32 v81, v82, v83
	v_mul_f32_e32 v82, 0xbfb8aa3b, v76
	v_mul_f32_e32 v83, 0xbfb8aa3b, v77
	v_exp_f32_e32 v82, v82
	v_exp_f32_e32 v83, v83
	global_store_dwordx2 v[96:97], v[80:81], off offset:32
	v_or_b32_e32 v80, 48, v122
	v_add_f32_e32 v82, 1.0, v82
	v_add_f32_e32 v83, 1.0, v83
	v_rcp_f32_e32 v82, v82
	v_rcp_f32_e32 v83, v83
	v_mad_i64_i32 v[80:81], s[2:3], v80, s46, v[120:121]
	v_pk_mul_f32 v[76:77], v[76:77], v[82:83]
	s_nop 0
	v_pk_mul_f32 v[72:73], v[72:73], v[76:77]
	s_nop 0
	v_cvt_pk_bf16_f32 v72, v72, v73
	v_mul_f32_e32 v73, 0xbfb8aa3b, v78
	v_exp_f32_e32 v73, v73
	s_nop 0
	v_add_f32_e32 v73, 1.0, v73
	v_rcp_f32_e32 v76, v73
	v_mul_f32_e32 v73, 0xbfb8aa3b, v79
	v_exp_f32_e32 v73, v73
	s_nop 0
	v_add_f32_e32 v73, 1.0, v73
	v_rcp_f32_e32 v77, v73
	s_nop 0
	v_pk_mul_f32 v[76:77], v[78:79], v[76:77]
	s_nop 0
	v_pk_mul_f32 v[74:75], v[74:75], v[76:77]
	s_nop 0
	v_cvt_pk_bf16_f32 v73, v74, v75
	global_store_dwordx2 v[80:81], v[72:73], off
	v_mul_f32_e32 v72, 0xbfb8aa3b, v68
	v_mul_f32_e32 v73, 0xbfb8aa3b, v69
	v_exp_f32_e32 v72, v72
	v_exp_f32_e32 v73, v73
	v_add_f32_e32 v72, 1.0, v72
	v_add_f32_e32 v73, 1.0, v73
	v_rcp_f32_e32 v72, v72
	v_rcp_f32_e32 v73, v73
	s_nop 0
	v_pk_mul_f32 v[68:69], v[68:69], v[72:73]
	s_nop 0
	v_pk_mul_f32 v[64:65], v[64:65], v[68:69]
	s_nop 0
	v_cvt_pk_bf16_f32 v64, v64, v65
	v_mul_f32_e32 v65, 0xbfb8aa3b, v70
	v_exp_f32_e32 v65, v65
	s_nop 0
	v_add_f32_e32 v65, 1.0, v65
	v_rcp_f32_e32 v68, v65
	v_mul_f32_e32 v65, 0xbfb8aa3b, v71
	v_exp_f32_e32 v65, v65
	s_nop 0
	v_add_f32_e32 v65, 1.0, v65
	v_rcp_f32_e32 v69, v65
	s_nop 0
	v_pk_mul_f32 v[68:69], v[70:71], v[68:69]
	s_nop 0
	v_pk_mul_f32 v[66:67], v[66:67], v[68:69]
	s_nop 0
	v_cvt_pk_bf16_f32 v65, v66, v67
	v_mul_f32_e32 v66, 0xbfb8aa3b, v60
	v_mul_f32_e32 v67, 0xbfb8aa3b, v61
	v_exp_f32_e32 v66, v66
	v_exp_f32_e32 v67, v67
	global_store_dwordx2 v[80:81], v[64:65], off offset:32
	v_or_b32_e32 v64, 64, v122
	v_add_f32_e32 v66, 1.0, v66
	v_add_f32_e32 v67, 1.0, v67
	v_rcp_f32_e32 v66, v66
	v_rcp_f32_e32 v67, v67
	v_mad_i64_i32 v[64:65], s[2:3], v64, s46, v[120:121]
	v_pk_mul_f32 v[60:61], v[60:61], v[66:67]
	s_nop 0
	v_pk_mul_f32 v[56:57], v[56:57], v[60:61]
	s_nop 0
	v_cvt_pk_bf16_f32 v56, v56, v57
	v_mul_f32_e32 v57, 0xbfb8aa3b, v62
	v_exp_f32_e32 v57, v57
	s_nop 0
	v_add_f32_e32 v57, 1.0, v57
	v_rcp_f32_e32 v60, v57
	v_mul_f32_e32 v57, 0xbfb8aa3b, v63
	v_exp_f32_e32 v57, v57
	s_nop 0
	v_add_f32_e32 v57, 1.0, v57
	v_rcp_f32_e32 v61, v57
	s_nop 0
	v_pk_mul_f32 v[60:61], v[62:63], v[60:61]
	s_nop 0
	v_pk_mul_f32 v[58:59], v[58:59], v[60:61]
	s_nop 0
	v_cvt_pk_bf16_f32 v57, v58, v59
	global_store_dwordx2 v[64:65], v[56:57], off
	v_mul_f32_e32 v56, 0xbfb8aa3b, v52
	v_mul_f32_e32 v57, 0xbfb8aa3b, v53
	v_exp_f32_e32 v56, v56
	v_exp_f32_e32 v57, v57
	v_add_f32_e32 v56, 1.0, v56
	v_add_f32_e32 v57, 1.0, v57
	v_rcp_f32_e32 v56, v56
	v_rcp_f32_e32 v57, v57
	s_nop 0
	v_pk_mul_f32 v[52:53], v[52:53], v[56:57]
	s_nop 0
	v_pk_mul_f32 v[48:49], v[48:49], v[52:53]
	s_nop 0
	v_cvt_pk_bf16_f32 v48, v48, v49
	v_mul_f32_e32 v49, 0xbfb8aa3b, v54
	v_exp_f32_e32 v49, v49
	s_nop 0
	v_add_f32_e32 v49, 1.0, v49
	v_rcp_f32_e32 v52, v49
	v_mul_f32_e32 v49, 0xbfb8aa3b, v55
	v_exp_f32_e32 v49, v49
	s_nop 0
	v_add_f32_e32 v49, 1.0, v49
	v_rcp_f32_e32 v53, v49
	s_nop 0
	v_pk_mul_f32 v[52:53], v[54:55], v[52:53]
	s_nop 0
	v_pk_mul_f32 v[50:51], v[50:51], v[52:53]
	s_nop 0
	v_cvt_pk_bf16_f32 v49, v50, v51
	v_mul_f32_e32 v50, 0xbfb8aa3b, v44
	v_mul_f32_e32 v51, 0xbfb8aa3b, v45
	v_exp_f32_e32 v50, v50
	v_exp_f32_e32 v51, v51
	global_store_dwordx2 v[64:65], v[48:49], off offset:32
	v_or_b32_e32 v48, 0x50, v122
	v_add_f32_e32 v50, 1.0, v50
	v_add_f32_e32 v51, 1.0, v51
	v_rcp_f32_e32 v50, v50
	v_rcp_f32_e32 v51, v51
	v_mad_i64_i32 v[48:49], s[2:3], v48, s46, v[120:121]
	v_pk_mul_f32 v[44:45], v[44:45], v[50:51]
	s_nop 0
	v_pk_mul_f32 v[40:41], v[40:41], v[44:45]
	s_nop 0
	v_cvt_pk_bf16_f32 v40, v40, v41
	v_mul_f32_e32 v41, 0xbfb8aa3b, v46
	v_exp_f32_e32 v41, v41
	s_nop 0
	v_add_f32_e32 v41, 1.0, v41
	v_rcp_f32_e32 v44, v41
	v_mul_f32_e32 v41, 0xbfb8aa3b, v47
	v_exp_f32_e32 v41, v41
	s_nop 0
	v_add_f32_e32 v41, 1.0, v41
	v_rcp_f32_e32 v45, v41
	s_nop 0
	v_pk_mul_f32 v[44:45], v[46:47], v[44:45]
	s_nop 0
	v_pk_mul_f32 v[42:43], v[42:43], v[44:45]
	s_nop 0
	v_cvt_pk_bf16_f32 v41, v42, v43
	global_store_dwordx2 v[48:49], v[40:41], off
	v_mul_f32_e32 v40, 0xbfb8aa3b, v36
	v_mul_f32_e32 v41, 0xbfb8aa3b, v37
	v_exp_f32_e32 v40, v40
	v_exp_f32_e32 v41, v41
	v_add_f32_e32 v40, 1.0, v40
	v_add_f32_e32 v41, 1.0, v41
	v_rcp_f32_e32 v40, v40
	v_rcp_f32_e32 v41, v41
	s_nop 0
	v_pk_mul_f32 v[36:37], v[36:37], v[40:41]
	s_nop 0
	v_pk_mul_f32 v[32:33], v[32:33], v[36:37]
	s_nop 0
	v_cvt_pk_bf16_f32 v32, v32, v33
	v_mul_f32_e32 v33, 0xbfb8aa3b, v38
	v_exp_f32_e32 v33, v33
	s_nop 0
	v_add_f32_e32 v33, 1.0, v33
	v_rcp_f32_e32 v36, v33
	v_mul_f32_e32 v33, 0xbfb8aa3b, v39
	v_exp_f32_e32 v33, v33
	s_nop 0
	v_add_f32_e32 v33, 1.0, v33
	v_rcp_f32_e32 v37, v33
	s_nop 0
	v_pk_mul_f32 v[36:37], v[38:39], v[36:37]
	s_nop 0
	v_pk_mul_f32 v[34:35], v[34:35], v[36:37]
	s_nop 0
	v_cvt_pk_bf16_f32 v33, v34, v35
	v_mul_f32_e32 v34, 0xbfb8aa3b, v28
	v_mul_f32_e32 v35, 0xbfb8aa3b, v29
	v_exp_f32_e32 v34, v34
	v_exp_f32_e32 v35, v35
	global_store_dwordx2 v[48:49], v[32:33], off offset:32
	v_or_b32_e32 v32, 0x60, v122
	v_add_f32_e32 v34, 1.0, v34
	v_add_f32_e32 v35, 1.0, v35
	v_rcp_f32_e32 v34, v34
	v_rcp_f32_e32 v35, v35
	v_mad_i64_i32 v[32:33], s[2:3], v32, s46, v[120:121]
	v_pk_mul_f32 v[28:29], v[28:29], v[34:35]
	s_nop 0
	v_pk_mul_f32 v[24:25], v[24:25], v[28:29]
	s_nop 0
	v_cvt_pk_bf16_f32 v24, v24, v25
	v_mul_f32_e32 v25, 0xbfb8aa3b, v30
	v_exp_f32_e32 v25, v25
	s_nop 0
	v_add_f32_e32 v25, 1.0, v25
	v_rcp_f32_e32 v28, v25
	v_mul_f32_e32 v25, 0xbfb8aa3b, v31
	v_exp_f32_e32 v25, v25
	s_nop 0
	v_add_f32_e32 v25, 1.0, v25
	v_rcp_f32_e32 v29, v25
	s_nop 0
	v_pk_mul_f32 v[28:29], v[30:31], v[28:29]
	s_nop 0
	v_pk_mul_f32 v[26:27], v[26:27], v[28:29]
	s_nop 0
	v_cvt_pk_bf16_f32 v25, v26, v27
	global_store_dwordx2 v[32:33], v[24:25], off
	v_mul_f32_e32 v24, 0xbfb8aa3b, v20
	v_mul_f32_e32 v25, 0xbfb8aa3b, v21
	v_exp_f32_e32 v24, v24
	v_exp_f32_e32 v25, v25
	v_add_f32_e32 v24, 1.0, v24
	v_add_f32_e32 v25, 1.0, v25
	v_rcp_f32_e32 v24, v24
	v_rcp_f32_e32 v25, v25
	s_nop 0
	v_pk_mul_f32 v[20:21], v[20:21], v[24:25]
	s_nop 0
	v_pk_mul_f32 v[16:17], v[16:17], v[20:21]
	s_nop 0
	v_cvt_pk_bf16_f32 v16, v16, v17
	v_mul_f32_e32 v17, 0xbfb8aa3b, v22
	v_exp_f32_e32 v17, v17
	s_nop 0
	v_add_f32_e32 v17, 1.0, v17
	v_rcp_f32_e32 v20, v17
	v_mul_f32_e32 v17, 0xbfb8aa3b, v23
	v_exp_f32_e32 v17, v17
	s_nop 0
	v_add_f32_e32 v17, 1.0, v17
	v_rcp_f32_e32 v21, v17
	s_nop 0
	v_pk_mul_f32 v[20:21], v[22:23], v[20:21]
	s_nop 0
	v_pk_mul_f32 v[18:19], v[18:19], v[20:21]
	s_nop 0
	v_cvt_pk_bf16_f32 v17, v18, v19
	v_mul_f32_e32 v18, 0xbfb8aa3b, v12
	v_mul_f32_e32 v19, 0xbfb8aa3b, v13
	v_exp_f32_e32 v18, v18
	v_exp_f32_e32 v19, v19
	global_store_dwordx2 v[32:33], v[16:17], off offset:32
	v_or_b32_e32 v16, 0x70, v122
	v_add_f32_e32 v18, 1.0, v18
	v_add_f32_e32 v19, 1.0, v19
	v_rcp_f32_e32 v18, v18
	v_rcp_f32_e32 v19, v19
	v_mad_i64_i32 v[16:17], s[2:3], v16, s46, v[120:121]
	v_readlane_b32 s2, v254, 22
	v_pk_mul_f32 v[12:13], v[12:13], v[18:19]
	s_add_i32 s10, s10, s2
	v_pk_mul_f32 v[8:9], v[8:9], v[12:13]
	s_cmpk_gt_u32 s12, 0x15f
	v_cvt_pk_bf16_f32 v8, v8, v9
	v_mul_f32_e32 v9, 0xbfb8aa3b, v14
	v_exp_f32_e32 v9, v9
	s_nop 0
	v_add_f32_e32 v9, 1.0, v9
	v_rcp_f32_e32 v12, v9
	v_mul_f32_e32 v9, 0xbfb8aa3b, v15
	v_exp_f32_e32 v9, v9
	s_nop 0
	v_add_f32_e32 v9, 1.0, v9
	v_rcp_f32_e32 v13, v9
	s_nop 0
	v_pk_mul_f32 v[12:13], v[14:15], v[12:13]
	s_nop 0
	v_pk_mul_f32 v[10:11], v[10:11], v[12:13]
	s_nop 0
	v_cvt_pk_bf16_f32 v9, v10, v11
	global_store_dwordx2 v[16:17], v[8:9], off
	v_mul_f32_e32 v8, 0xbfb8aa3b, v4
	v_mul_f32_e32 v9, 0xbfb8aa3b, v5
	v_exp_f32_e32 v8, v8
	v_exp_f32_e32 v9, v9
	v_add_f32_e32 v8, 1.0, v8
	v_add_f32_e32 v9, 1.0, v9
	v_rcp_f32_e32 v8, v8
	v_rcp_f32_e32 v9, v9
	s_nop 0
	v_pk_mul_f32 v[4:5], v[4:5], v[8:9]
	s_nop 0
	v_pk_mul_f32 v[0:1], v[0:1], v[4:5]
	s_nop 0
	v_cvt_pk_bf16_f32 v0, v0, v1
	v_mul_f32_e32 v1, 0xbfb8aa3b, v6
	v_exp_f32_e32 v1, v1
	s_nop 0
	v_add_f32_e32 v1, 1.0, v1
	v_rcp_f32_e32 v4, v1
	v_mul_f32_e32 v1, 0xbfb8aa3b, v7
	v_exp_f32_e32 v1, v1
	s_nop 0
	v_add_f32_e32 v1, 1.0, v1
	v_rcp_f32_e32 v5, v1
	s_nop 0
	v_pk_mul_f32 v[4:5], v[6:7], v[4:5]
	s_nop 0
	v_pk_mul_f32 v[2:3], v[2:3], v[4:5]
	s_nop 0
	v_cvt_pk_bf16_f32 v1, v2, v3
	global_store_dwordx2 v[16:17], v[0:1], off offset:32
	s_cbranch_scc0 .LBB0_850

.LBB0_909:
	s_and_b32 s2, s14, 7
	s_or_b32 s2, s2, s33
	s_lshl_b32 s15, s2, 8
	v_add_u32_e32 v0, s15, v227
	s_lshl_b32 s2, s14, 4
	v_add_u32_e32 v1, 32, v0
	s_and_b32 s16, s2, 0x380
	v_mad_i64_i32 v[204:205], s[2:3], v1, s10, 0
	v_add_u32_e32 v1, 64, v0
	v_mad_i64_i32 v[206:207], s[2:3], v1, s10, 0
	v_add_u32_e32 v1, 0x60, v0
	v_mad_i64_i32 v[208:209], s[2:3], v1, s10, 0
	v_add_u32_e32 v1, 0x80, v0
	v_mad_i64_i32 v[210:211], s[2:3], v1, s10, 0
	v_add_u32_e32 v1, 0xa0, v0
	v_mad_i64_i32 v[202:203], s[2:3], v0, s10, 0
	v_mad_i64_i32 v[212:213], s[2:3], v1, s10, 0
	v_add_u32_e32 v1, 0xc0, v0
	v_add_u32_e32 v0, 0xe0, v0
	v_mad_i64_i32 v[216:217], s[2:3], v0, s10, 0
	v_add_u32_e32 v0, s16, v227
	v_mad_i64_i32 v[214:215], s[2:3], v1, s10, 0
	v_add_u32_e32 v1, 32, v0
	v_mad_i64_i32 v[218:219], s[2:3], v0, s10, 0
	v_mad_i64_i32 v[220:221], s[2:3], v1, s10, 0
	v_add_u32_e32 v1, 64, v0
	v_add_u32_e32 v0, 0x60, v0
	v_mad_i64_i32 v[222:223], s[2:3], v1, s10, 0
	v_mad_i64_i32 v[224:225], s[2:3], v0, s10, 0
	v_lshl_add_u64 v[0:1], v[224:225], 1, v[194:195]
	v_lshl_add_u64 v[4:5], v[222:223], 1, v[194:195]
	v_lshl_add_u64 v[8:9], v[220:221], 1, v[194:195]
	v_lshl_add_u64 v[12:13], v[218:219], 1, v[194:195]
	v_lshl_add_u64 v[16:17], v[216:217], 1, v[192:193]
	v_lshl_add_u64 v[20:21], v[214:215], 1, v[192:193]
	v_lshl_add_u64 v[24:25], v[212:213], 1, v[192:193]
	v_lshl_add_u64 v[28:29], v[210:211], 1, v[192:193]
	v_lshl_add_u64 v[32:33], v[208:209], 1, v[192:193]
	v_lshl_add_u64 v[36:37], v[206:207], 1, v[192:193]
	v_lshl_add_u64 v[40:41], v[204:205], 1, v[192:193]
	v_lshl_add_u64 v[44:45], v[202:203], 1, v[192:193]
	global_load_dwordx4 v[0:3], v[0:1], off sc1
	s_nop 0
	global_load_dwordx4 v[4:7], v[4:5], off sc1
	s_nop 0
	global_load_dwordx4 v[8:11], v[8:9], off sc1
	s_nop 0
	global_load_dwordx4 v[12:15], v[12:13], off sc1
	s_nop 0
	global_load_dwordx4 v[16:19], v[16:17], off sc1
	s_nop 0
	global_load_dwordx4 v[20:23], v[20:21], off sc1
	s_nop 0
	global_load_dwordx4 v[24:27], v[24:25], off sc1
	s_nop 0
	global_load_dwordx4 v[28:31], v[28:29], off sc1
	s_nop 0
	global_load_dwordx4 v[32:35], v[32:33], off sc1
	s_nop 0
	global_load_dwordx4 v[36:39], v[36:37], off sc1
	s_nop 0
	global_load_dwordx4 v[40:43], v[40:41], off sc1
	s_nop 0
	global_load_dwordx4 v[44:47], v[44:45], off sc1
	v_mov_b32_e32 v144, 0
	s_mov_b32 s50, 64
	s_mov_b32 s2, s13
	v_mov_b32_e32 v145, v144
	v_mov_b32_e32 v146, v144
	v_mov_b32_e32 v147, v144
	v_mov_b32_e32 v148, v144
	v_mov_b32_e32 v149, v144
	v_mov_b32_e32 v150, v144
	v_mov_b32_e32 v151, v144
	v_mov_b32_e32 v152, v144
	v_mov_b32_e32 v153, v144
	v_mov_b32_e32 v154, v144
	v_mov_b32_e32 v155, v144
	v_mov_b32_e32 v156, v144
	v_mov_b32_e32 v157, v144
	v_mov_b32_e32 v158, v144
	v_mov_b32_e32 v159, v144
	v_mov_b32_e32 v116, v144
	v_mov_b32_e32 v117, v144
	v_mov_b32_e32 v118, v144
	v_mov_b32_e32 v119, v144
	v_mov_b32_e32 v128, v144
	v_mov_b32_e32 v129, v144
	v_mov_b32_e32 v130, v144
	v_mov_b32_e32 v131, v144
	v_mov_b32_e32 v136, v144
	v_mov_b32_e32 v137, v144
	v_mov_b32_e32 v138, v144
	v_mov_b32_e32 v139, v144
	v_mov_b32_e32 v140, v144
	v_mov_b32_e32 v141, v144
	v_mov_b32_e32 v142, v144
	v_mov_b32_e32 v143, v144
	v_mov_b32_e32 v100, v144
	v_mov_b32_e32 v101, v144
	v_mov_b32_e32 v102, v144
	v_mov_b32_e32 v103, v144
	v_mov_b32_e32 v112, v144
	v_mov_b32_e32 v113, v144
	v_mov_b32_e32 v114, v144
	v_mov_b32_e32 v115, v144
	v_mov_b32_e32 v124, v144
	v_mov_b32_e32 v125, v144
	v_mov_b32_e32 v126, v144
	v_mov_b32_e32 v127, v144
	v_mov_b32_e32 v132, v144
	v_mov_b32_e32 v133, v144
	v_mov_b32_e32 v134, v144
	v_mov_b32_e32 v135, v144
	v_mov_b32_e32 v88, v144
	v_mov_b32_e32 v89, v144
	v_mov_b32_e32 v90, v144
	v_mov_b32_e32 v91, v144
	v_mov_b32_e32 v96, v144
	v_mov_b32_e32 v97, v144
	v_mov_b32_e32 v98, v144
	v_mov_b32_e32 v99, v144
	v_mov_b32_e32 v108, v144
	v_mov_b32_e32 v109, v144
	v_mov_b32_e32 v110, v144
	v_mov_b32_e32 v111, v144
	v_mov_b32_e32 v120, v144
	v_mov_b32_e32 v121, v144
	v_mov_b32_e32 v122, v144
	v_mov_b32_e32 v123, v144
	v_mov_b32_e32 v80, v144
	v_mov_b32_e32 v81, v144
	v_mov_b32_e32 v82, v144
	v_mov_b32_e32 v83, v144
	v_mov_b32_e32 v84, v144
	v_mov_b32_e32 v85, v144
	v_mov_b32_e32 v86, v144
	v_mov_b32_e32 v87, v144
	v_mov_b32_e32 v92, v144
	v_mov_b32_e32 v93, v144
	v_mov_b32_e32 v94, v144
	v_mov_b32_e32 v95, v144
	v_mov_b32_e32 v104, v144
	v_mov_b32_e32 v105, v144
	v_mov_b32_e32 v106, v144
	v_mov_b32_e32 v107, v144
	v_mov_b32_e32 v48, v144
	v_mov_b32_e32 v49, v144
	v_mov_b32_e32 v50, v144
	v_mov_b32_e32 v51, v144
	v_mov_b32_e32 v52, v144
	v_mov_b32_e32 v53, v144
	v_mov_b32_e32 v54, v144
	v_mov_b32_e32 v55, v144
	v_mov_b32_e32 v56, v144
	v_mov_b32_e32 v57, v144
	v_mov_b32_e32 v58, v144
	v_mov_b32_e32 v59, v144
	v_mov_b32_e32 v72, v144
	v_mov_b32_e32 v73, v144
	v_mov_b32_e32 v74, v144
	v_mov_b32_e32 v75, v144
	v_mov_b32_e32 v76, v144
	v_mov_b32_e32 v77, v144
	v_mov_b32_e32 v78, v144
	v_mov_b32_e32 v79, v144
	v_mov_b32_e32 v68, v144
	v_mov_b32_e32 v69, v144
	v_mov_b32_e32 v70, v144
	v_mov_b32_e32 v71, v144
	v_mov_b32_e32 v64, v144
	v_mov_b32_e32 v65, v144
	v_mov_b32_e32 v66, v144
	v_mov_b32_e32 v67, v144
	v_mov_b32_e32 v60, v144
	v_mov_b32_e32 v61, v144
	v_mov_b32_e32 v62, v144
	v_mov_b32_e32 v63, v144
	v_mov_b32_e32 v160, v144
	v_mov_b32_e32 v161, v144
	v_mov_b32_e32 v162, v144
	v_mov_b32_e32 v163, v144
	v_mov_b32_e32 v164, v144
	v_mov_b32_e32 v165, v144
	v_mov_b32_e32 v166, v144
	v_mov_b32_e32 v167, v144
	v_mov_b32_e32 v168, v144
	v_mov_b32_e32 v169, v144
	v_mov_b32_e32 v170, v144
	v_mov_b32_e32 v171, v144
	v_mov_b32_e32 v172, v144
	v_mov_b32_e32 v173, v144
	v_mov_b32_e32 v174, v144
	v_mov_b32_e32 v175, v144
	v_readlane_b32 s84, v252, 0
	s_cmp_ge_u32 s84, 0x100
	s_cbranch_scc0 .Lgprio_3
	s_setprio 1
.Lgprio_3:
.LBB0_910:
	s_lshl_b64 s[8:9], s[50:51], 1
	s_waitcnt vmcnt(63) expcnt(7) lgkmcnt(15)
	s_barrier
	s_waitcnt vmcnt(0)
	ds_write_b128 v240, v[44:47]
	ds_write_b128 v240, v[40:43] offset:5120
	ds_write_b128 v240, v[36:39] offset:10240
	ds_write_b128 v240, v[32:35] offset:15360
	ds_write_b128 v240, v[28:31] offset:20480
	ds_write_b128 v240, v[24:27] offset:25600
	ds_write_b128 v240, v[20:23] offset:30720
	ds_write_b128 v240, v[16:19] offset:35840
	ds_write_b128 v240, v[12:15] offset:40960
	ds_write_b128 v240, v[8:11] offset:46080
	ds_write_b128 v240, v[4:7] offset:51200
	ds_write_b128 v240, v[0:3] offset:56320
	v_lshl_add_u64 v[0:1], v[192:193], 0, s[8:9]
	v_lshl_add_u64 v[2:3], v[194:195], 0, s[8:9]
	v_lshl_add_u64 v[4:5], v[202:203], 1, v[0:1]
	v_lshl_add_u64 v[6:7], v[204:205], 1, v[0:1]
	v_lshl_add_u64 v[8:9], v[206:207], 1, v[0:1]
	v_lshl_add_u64 v[10:11], v[208:209], 1, v[0:1]
	v_lshl_add_u64 v[12:13], v[210:211], 1, v[0:1]
	v_lshl_add_u64 v[14:15], v[212:213], 1, v[0:1]
	v_lshl_add_u64 v[16:17], v[214:215], 1, v[0:1]
	v_lshl_add_u64 v[0:1], v[216:217], 1, v[0:1]
	v_lshl_add_u64 v[176:177], v[218:219], 1, v[2:3]
	v_lshl_add_u64 v[178:179], v[220:221], 1, v[2:3]
	v_lshl_add_u64 v[180:181], v[222:223], 1, v[2:3]
	v_lshl_add_u64 v[2:3], v[224:225], 1, v[2:3]
	s_waitcnt lgkmcnt(0)
	s_barrier
	global_load_dwordx4 v[44:47], v[4:5], off sc1
	global_load_dwordx4 v[40:43], v[6:7], off sc1
	global_load_dwordx4 v[36:39], v[8:9], off sc1
	global_load_dwordx4 v[32:35], v[10:11], off sc1
	global_load_dwordx4 v[28:31], v[12:13], off sc1
	global_load_dwordx4 v[24:27], v[14:15], off sc1
	global_load_dwordx4 v[20:23], v[16:17], off sc1
	s_nop 0
	global_load_dwordx4 v[16:19], v[0:1], off sc1
	global_load_dwordx4 v[12:15], v[176:177], off sc1
	global_load_dwordx4 v[8:11], v[178:179], off sc1
	global_load_dwordx4 v[4:7], v[180:181], off sc1
	s_nop 0
	global_load_dwordx4 v[0:3], v[2:3], off sc1
	ds_read_b128 v[176:179], v241 offset:40960
	ds_read_b128 v[184:187], v241 offset:43520
	ds_read_b128 v[188:191], v241 offset:46080
	ds_read_b128 v[230:233], v241 offset:48640
	ds_read_b128 v[180:183], v239
	ds_read_b128 v[244:247], v239 offset:2560
	s_add_i32 s2, s2, -1
	s_add_i32 s50, s50, 64
	s_waitcnt lgkmcnt(1)
	v_mfma_f32_16x16x32_bf16 v[60:63], v[176:179], v[180:183], v[60:63]
	v_mfma_f32_16x16x32_bf16 v[64:67], v[184:187], v[180:183], v[64:67]
	v_mfma_f32_16x16x32_bf16 v[68:71], v[188:191], v[180:183], v[68:71]
	v_mfma_f32_16x16x32_bf16 v[76:79], v[230:233], v[180:183], v[76:79]
	ds_read_b128 v[180:183], v239 offset:5120
	s_waitcnt lgkmcnt(1)
	v_mfma_f32_16x16x32_bf16 v[72:75], v[176:179], v[244:247], v[72:75]
	v_mfma_f32_16x16x32_bf16 v[56:59], v[184:187], v[244:247], v[56:59]
	v_mfma_f32_16x16x32_bf16 v[52:55], v[188:191], v[244:247], v[52:55]
	v_mfma_f32_16x16x32_bf16 v[48:51], v[230:233], v[244:247], v[48:51]
	ds_read_b128 v[244:247], v239 offset:7680
	s_waitcnt lgkmcnt(1)
	v_mfma_f32_16x16x32_bf16 v[104:107], v[176:179], v[180:183], v[104:107]
	v_mfma_f32_16x16x32_bf16 v[92:95], v[184:187], v[180:183], v[92:95]
	v_mfma_f32_16x16x32_bf16 v[84:87], v[188:191], v[180:183], v[84:87]
	v_mfma_f32_16x16x32_bf16 v[80:83], v[230:233], v[180:183], v[80:83]
	ds_read_b128 v[180:183], v239 offset:10240
	s_waitcnt lgkmcnt(1)
	v_mfma_f32_16x16x32_bf16 v[120:123], v[176:179], v[244:247], v[120:123]
	v_mfma_f32_16x16x32_bf16 v[108:111], v[184:187], v[244:247], v[108:111]
	v_mfma_f32_16x16x32_bf16 v[96:99], v[188:191], v[244:247], v[96:99]
	v_mfma_f32_16x16x32_bf16 v[88:91], v[230:233], v[244:247], v[88:91]
	ds_read_b128 v[244:247], v239 offset:12800
	s_waitcnt lgkmcnt(1)
	v_mfma_f32_16x16x32_bf16 v[132:135], v[176:179], v[180:183], v[132:135]
	v_mfma_f32_16x16x32_bf16 v[124:127], v[184:187], v[180:183], v[124:127]
	v_mfma_f32_16x16x32_bf16 v[112:115], v[188:191], v[180:183], v[112:115]
	v_mfma_f32_16x16x32_bf16 v[100:103], v[230:233], v[180:183], v[100:103]
	ds_read_b128 v[180:183], v239 offset:15360
	s_waitcnt lgkmcnt(1)
	v_mfma_f32_16x16x32_bf16 v[140:143], v[176:179], v[244:247], v[140:143]
	v_mfma_f32_16x16x32_bf16 v[136:139], v[184:187], v[244:247], v[136:139]
	v_mfma_f32_16x16x32_bf16 v[128:131], v[188:191], v[244:247], v[128:131]
	v_mfma_f32_16x16x32_bf16 v[116:119], v[230:233], v[244:247], v[116:119]
	ds_read_b128 v[244:247], v242
	s_waitcnt lgkmcnt(1)
	v_mfma_f32_16x16x32_bf16 v[156:159], v[176:179], v[180:183], v[156:159]
	v_mfma_f32_16x16x32_bf16 v[152:155], v[184:187], v[180:183], v[152:155]
	v_mfma_f32_16x16x32_bf16 v[148:151], v[188:191], v[180:183], v[148:151]
	v_mfma_f32_16x16x32_bf16 v[144:147], v[230:233], v[180:183], v[144:147]
	ds_read_b128 v[180:183], v239 offset:64
	s_waitcnt lgkmcnt(1)
	v_mfma_f32_16x16x32_bf16 v[160:163], v[176:179], v[244:247], v[160:163]
	ds_read_b128 v[176:179], v241 offset:41024
	v_mfma_f32_16x16x32_bf16 v[164:167], v[184:187], v[244:247], v[164:167]
	ds_read_b128 v[184:187], v241 offset:43584
	v_mfma_f32_16x16x32_bf16 v[168:171], v[188:191], v[244:247], v[168:171]
	ds_read_b128 v[188:191], v241 offset:46144
	v_mfma_f32_16x16x32_bf16 v[172:175], v[230:233], v[244:247], v[172:175]
	ds_read_b128 v[230:233], v241 offset:48704
	ds_read_b128 v[244:247], v239 offset:2624
	s_waitcnt lgkmcnt(1)
	v_mfma_f32_16x16x32_bf16 v[60:63], v[176:179], v[180:183], v[60:63]
	v_mfma_f32_16x16x32_bf16 v[64:67], v[184:187], v[180:183], v[64:67]
	v_mfma_f32_16x16x32_bf16 v[68:71], v[188:191], v[180:183], v[68:71]
	v_mfma_f32_16x16x32_bf16 v[76:79], v[230:233], v[180:183], v[76:79]
	ds_read_b128 v[180:183], v239 offset:5184
	s_waitcnt lgkmcnt(1)
	v_mfma_f32_16x16x32_bf16 v[72:75], v[176:179], v[244:247], v[72:75]
	v_mfma_f32_16x16x32_bf16 v[56:59], v[184:187], v[244:247], v[56:59]
	v_mfma_f32_16x16x32_bf16 v[52:55], v[188:191], v[244:247], v[52:55]
	v_mfma_f32_16x16x32_bf16 v[48:51], v[230:233], v[244:247], v[48:51]
	ds_read_b128 v[244:247], v239 offset:7744
	s_waitcnt lgkmcnt(1)
	v_mfma_f32_16x16x32_bf16 v[104:107], v[176:179], v[180:183], v[104:107]
	v_mfma_f32_16x16x32_bf16 v[92:95], v[184:187], v[180:183], v[92:95]
	v_mfma_f32_16x16x32_bf16 v[84:87], v[188:191], v[180:183], v[84:87]
	v_mfma_f32_16x16x32_bf16 v[80:83], v[230:233], v[180:183], v[80:83]
	ds_read_b128 v[180:183], v239 offset:10304
	s_waitcnt lgkmcnt(1)
	v_mfma_f32_16x16x32_bf16 v[120:123], v[176:179], v[244:247], v[120:123]
	v_mfma_f32_16x16x32_bf16 v[108:111], v[184:187], v[244:247], v[108:111]
	v_mfma_f32_16x16x32_bf16 v[96:99], v[188:191], v[244:247], v[96:99]
	v_mfma_f32_16x16x32_bf16 v[88:91], v[230:233], v[244:247], v[88:91]
	ds_read_b128 v[244:247], v239 offset:12864
	s_waitcnt lgkmcnt(1)
	v_mfma_f32_16x16x32_bf16 v[132:135], v[176:179], v[180:183], v[132:135]
	v_mfma_f32_16x16x32_bf16 v[124:127], v[184:187], v[180:183], v[124:127]
	v_mfma_f32_16x16x32_bf16 v[112:115], v[188:191], v[180:183], v[112:115]
	v_mfma_f32_16x16x32_bf16 v[100:103], v[230:233], v[180:183], v[100:103]
	ds_read_b128 v[180:183], v239 offset:15424
	s_waitcnt lgkmcnt(1)
	v_mfma_f32_16x16x32_bf16 v[140:143], v[176:179], v[244:247], v[140:143]
	v_mfma_f32_16x16x32_bf16 v[136:139], v[184:187], v[244:247], v[136:139]
	v_mfma_f32_16x16x32_bf16 v[128:131], v[188:191], v[244:247], v[128:131]
	v_mfma_f32_16x16x32_bf16 v[116:119], v[230:233], v[244:247], v[116:119]
	ds_read_b128 v[244:247], v242 offset:64
	s_waitcnt lgkmcnt(1)
	v_mfma_f32_16x16x32_bf16 v[156:159], v[176:179], v[180:183], v[156:159]
	v_mfma_f32_16x16x32_bf16 v[152:155], v[184:187], v[180:183], v[152:155]
	v_mfma_f32_16x16x32_bf16 v[148:151], v[188:191], v[180:183], v[148:151]
	v_mfma_f32_16x16x32_bf16 v[144:147], v[230:233], v[180:183], v[144:147]
	s_waitcnt lgkmcnt(0)
	v_mfma_f32_16x16x32_bf16 v[160:163], v[176:179], v[244:247], v[160:163]
	v_mfma_f32_16x16x32_bf16 v[164:167], v[184:187], v[244:247], v[164:167]
	v_mfma_f32_16x16x32_bf16 v[168:171], v[188:191], v[244:247], v[168:171]
	v_mfma_f32_16x16x32_bf16 v[172:175], v[230:233], v[244:247], v[172:175]
	s_cmp_eq_u32 s2, 0
	s_cbranch_scc0 .LBB0_910
	s_setprio 0
	s_add_i32 s2, s15, 0xffffe000
	s_ashr_i32 s2, s2, 12
	s_mulk_i32 s2, 0x1800
	s_add_i32 s8, s2, 0x1800
	s_and_b64 s[2:3], s[18:19], exec
	s_cselect_b32 s8, 0, s8
	s_ashr_i32 s9, s8, 31
	s_barrier
	s_waitcnt vmcnt(11)
	ds_write_b128 v240, v[44:47]
	s_waitcnt vmcnt(10)
	ds_write_b128 v240, v[40:43] offset:5120
	s_waitcnt vmcnt(9)
	ds_write_b128 v240, v[36:39] offset:10240
	s_waitcnt vmcnt(8)
	ds_write_b128 v240, v[32:35] offset:15360
	s_waitcnt vmcnt(7)
	ds_write_b128 v240, v[28:31] offset:20480
	s_waitcnt vmcnt(6)
	ds_write_b128 v240, v[24:27] offset:25600
	s_waitcnt vmcnt(5)
	ds_write_b128 v240, v[20:23] offset:30720
	s_waitcnt vmcnt(4)
	ds_write_b128 v240, v[16:19] offset:35840
	s_waitcnt vmcnt(3)
	ds_write_b128 v240, v[12:15] offset:40960
	s_waitcnt vmcnt(2)
	ds_write_b128 v240, v[8:11] offset:46080
	s_waitcnt vmcnt(1)
	ds_write_b128 v240, v[4:7] offset:51200
	s_waitcnt vmcnt(0)
	ds_write_b128 v240, v[0:3] offset:56320
	s_waitcnt lgkmcnt(0)
	s_barrier
	ds_read_b128 v[0:3], v241 offset:40960
	ds_read_b128 v[4:7], v241 offset:43520
	ds_read_b128 v[8:11], v241 offset:46080
	ds_read_b128 v[12:15], v241 offset:48640
	ds_read_b128 v[16:19], v239 offset:2560
	ds_read_b128 v[20:23], v239 offset:5120
	ds_read_b128 v[24:27], v239
	ds_read_b128 v[40:43], v239 offset:7680
	s_lshl_b64 s[2:3], s[8:9], 2
	s_waitcnt lgkmcnt(3)
	v_mfma_f32_16x16x32_bf16 v[44:47], v[0:3], v[16:19], v[72:75]
	s_add_u32 s2, s11, s2
	s_addc_u32 s3, s12, s3
	v_mov_b32_e32 v201, v197
	s_waitcnt lgkmcnt(1)
	v_mfma_f32_16x16x32_bf16 v[28:31], v[0:3], v[24:27], v[60:63]
	ds_read_b128 v[72:75], v239 offset:12800
	s_add_i32 s14, s14, s53
	s_cmp_gt_u32 s14, 63
	v_mfma_f32_16x16x32_bf16 v[32:35], v[4:7], v[24:27], v[64:67]
	v_mfma_f32_16x16x32_bf16 v[36:39], v[8:11], v[24:27], v[68:71]
	v_mfma_f32_16x16x32_bf16 v[24:27], v[12:15], v[24:27], v[76:79]
	v_mfma_f32_16x16x32_bf16 v[56:59], v[4:7], v[16:19], v[56:59]
	v_mfma_f32_16x16x32_bf16 v[52:55], v[8:11], v[16:19], v[52:55]
	v_mfma_f32_16x16x32_bf16 v[16:19], v[12:15], v[16:19], v[48:51]
	s_nop 2
	ds_read_b128 v[48:51], v239 offset:10240
	v_mfma_f32_16x16x32_bf16 v[60:63], v[0:3], v[20:23], v[104:107]
	v_mfma_f32_16x16x32_bf16 v[64:67], v[4:7], v[20:23], v[92:95]
	v_mfma_f32_16x16x32_bf16 v[68:71], v[8:11], v[20:23], v[84:87]
	s_nop 1
	ds_read_b128 v[92:95], v242
	v_mfma_f32_16x16x32_bf16 v[20:23], v[12:15], v[20:23], v[80:83]
	s_waitcnt lgkmcnt(3)
	v_mfma_f32_16x16x32_bf16 v[76:79], v[0:3], v[40:43], v[120:123]
	v_mfma_f32_16x16x32_bf16 v[80:83], v[4:7], v[40:43], v[108:111]
	v_mfma_f32_16x16x32_bf16 v[84:87], v[8:11], v[40:43], v[96:99]
	v_mfma_f32_16x16x32_bf16 v[40:43], v[12:15], v[40:43], v[88:91]
	s_nop 2
	ds_read_b128 v[88:91], v239 offset:15360
	s_waitcnt lgkmcnt(2)
	v_mfma_f32_16x16x32_bf16 v[176:179], v[0:3], v[48:51], v[132:135]
	v_mfma_f32_16x16x32_bf16 v[180:183], v[4:7], v[48:51], v[124:127]
	v_mfma_f32_16x16x32_bf16 v[184:187], v[8:11], v[48:51], v[112:115]
	v_mfma_f32_16x16x32_bf16 v[48:51], v[12:15], v[48:51], v[100:103]
	v_mfma_f32_16x16x32_bf16 v[188:191], v[0:3], v[72:75], v[140:143]
	v_mfma_f32_16x16x32_bf16 v[202:205], v[4:7], v[72:75], v[136:139]
	v_mfma_f32_16x16x32_bf16 v[206:209], v[8:11], v[72:75], v[128:131]
	v_mfma_f32_16x16x32_bf16 v[210:213], v[12:15], v[72:75], v[116:119]
	s_waitcnt lgkmcnt(0)
	v_mfma_f32_16x16x32_bf16 v[156:159], v[0:3], v[88:91], v[156:159]
	v_mfma_f32_16x16x32_bf16 v[152:155], v[4:7], v[88:91], v[152:155]
	v_mfma_f32_16x16x32_bf16 v[148:151], v[8:11], v[88:91], v[148:151]
	v_mfma_f32_16x16x32_bf16 v[144:147], v[12:15], v[88:91], v[144:147]
	v_mfma_f32_16x16x32_bf16 v[0:3], v[0:3], v[92:95], v[160:163]
	v_mfma_f32_16x16x32_bf16 v[4:7], v[4:7], v[92:95], v[164:167]
	v_mfma_f32_16x16x32_bf16 v[8:11], v[8:11], v[92:95], v[168:171]
	v_mfma_f32_16x16x32_bf16 v[160:163], v[12:15], v[92:95], v[172:175]
	ds_read_b128 v[12:15], v241 offset:41024
	ds_read_b128 v[164:167], v241 offset:43584
	ds_read_b128 v[168:171], v241 offset:46144
	ds_read_b128 v[172:175], v241 offset:48704
	ds_read_b128 v[72:75], v239 offset:2624
	ds_read_b128 v[88:91], v239 offset:5184
	ds_read_b128 v[92:95], v239 offset:64
	s_waitcnt lgkmcnt(0)
	v_mfma_f32_16x16x32_bf16 v[128:131], v[172:175], v[92:95], v[24:27]
	s_nop 2
	ds_read_b128 v[24:27], v239 offset:7744
	v_mfma_f32_16x16x32_bf16 v[116:119], v[168:171], v[72:75], v[52:55]
	v_mfma_f32_16x16x32_bf16 v[112:115], v[172:175], v[72:75], v[16:19]
	s_nop 1
	ds_read_b128 v[52:55], v239 offset:15424
	ds_read_b128 v[16:19], v239 offset:10304
	v_mfma_f32_16x16x32_bf16 v[108:111], v[12:15], v[88:91], v[60:63]
	v_mfma_f32_16x16x32_bf16 v[96:99], v[172:175], v[88:91], v[20:23]
	s_nop 1
	ds_read_b128 v[60:63], v242 offset:64
	ds_read_b128 v[20:23], v239 offset:12864
	v_mfma_f32_16x16x32_bf16 v[140:143], v[12:15], v[92:95], v[28:31]
	v_mfma_f32_16x16x32_bf16 v[136:139], v[164:167], v[92:95], v[32:35]
	v_mfma_f32_16x16x32_bf16 v[132:135], v[168:171], v[92:95], v[36:39]
	v_mfma_f32_16x16x32_bf16 v[124:127], v[12:15], v[72:75], v[44:47]
	v_mfma_f32_16x16x32_bf16 v[120:123], v[164:167], v[72:75], v[56:59]
	v_mfma_f32_16x16x32_bf16 v[104:107], v[164:167], v[88:91], v[64:67]
	v_mfma_f32_16x16x32_bf16 v[100:103], v[168:171], v[88:91], v[68:71]
	s_waitcnt lgkmcnt(4)
	v_mfma_f32_16x16x32_bf16 v[92:95], v[12:15], v[24:27], v[76:79]
	v_mfma_f32_16x16x32_bf16 v[88:91], v[164:167], v[24:27], v[80:83]
	v_mfma_f32_16x16x32_bf16 v[80:83], v[172:175], v[24:27], v[40:43]
	s_waitcnt lgkmcnt(2)
	v_mfma_f32_16x16x32_bf16 v[76:79], v[12:15], v[16:19], v[176:179]
	v_mfma_f32_16x16x32_bf16 v[72:75], v[164:167], v[16:19], v[180:183]
	v_mfma_f32_16x16x32_bf16 v[64:67], v[168:171], v[16:19], v[184:187]
	v_mfma_f32_16x16x32_bf16 v[56:59], v[172:175], v[16:19], v[48:51]
	s_waitcnt lgkmcnt(0)
	v_mfma_f32_16x16x32_bf16 v[48:51], v[12:15], v[20:23], v[188:191]
	v_mfma_f32_16x16x32_bf16 v[44:47], v[164:167], v[20:23], v[202:205]
	v_mfma_f32_16x16x32_bf16 v[40:43], v[168:171], v[20:23], v[206:209]
	v_mfma_f32_16x16x32_bf16 v[36:39], v[172:175], v[20:23], v[210:213]
	v_mfma_f32_16x16x32_bf16 v[32:35], v[12:15], v[52:55], v[156:159]
	v_mfma_f32_16x16x32_bf16 v[20:23], v[172:175], v[52:55], v[144:147]
	v_mfma_f32_16x16x32_bf16 v[16:19], v[12:15], v[60:63], v[0:3]
	s_nop 1
	v_add_u32_e32 v146, s15, v238
	v_ashrrev_i32_e32 v147, 31, v146
	v_mfma_f32_16x16x32_bf16 v[12:15], v[164:167], v[60:63], v[4:7]
	s_nop 2
	v_or_b32_e32 v4, s16, v226
	v_lshlrev_b32_e32 v196, 2, v4
	v_mfma_f32_16x16x32_bf16 v[84:87], v[168:171], v[24:27], v[84:87]
	v_lshl_add_u64 v[4:5], s[2:3], 0, v[196:197]
	v_lshl_add_u64 v[144:145], v[198:199], 0, v[196:197]
	v_lshl_add_u64 v[4:5], v[4:5], 0, v[200:201]
	v_mfma_f32_16x16x32_bf16 v[24:27], v[168:171], v[52:55], v[148:151]
	s_nop 2
	v_lshlrev_b64 v[148:149], 12, v[146:147]
	v_mfma_f32_16x16x32_bf16 v[28:31], v[164:167], v[52:55], v[152:155]
	s_nop 2
	v_lshl_add_u64 v[152:153], v[144:145], 0, v[148:149]
	v_mfma_f32_16x16x32_bf16 v[8:11], v[168:171], v[60:63], v[8:11]
	v_mfma_f32_16x16x32_bf16 v[0:3], v[172:175], v[60:63], v[160:163]
	global_load_dwordx4 v[68:71], v[4:5], off sc1
	global_load_dwordx4 v[60:63], v[4:5], off offset:64 sc1
	global_load_dwordx4 v[52:55], v[4:5], off offset:128 sc1
	s_nop 0
	global_load_dwordx4 v[4:7], v[4:5], off offset:192 sc1
	s_nop 0
	global_load_dwordx4 v[148:151], v[152:153], off sc1
	s_waitcnt vmcnt(0)
	v_pk_fma_f32 v[142:143], v[142:143], v[70:71], v[150:151]
	v_pk_fma_f32 v[140:141], v[140:141], v[68:69], v[148:149]
	global_store_dwordx4 v[152:153], v[140:143], off
	global_load_dwordx4 v[140:143], v[152:153], off offset:64 sc1
	s_waitcnt vmcnt(0)
	v_pk_fma_f32 v[138:139], v[138:139], v[62:63], v[142:143]
	v_pk_fma_f32 v[136:137], v[136:137], v[60:61], v[140:141]
	global_store_dwordx4 v[152:153], v[136:139], off offset:64
	global_load_dwordx4 v[136:139], v[152:153], off offset:128 sc1
	s_waitcnt vmcnt(0)
	v_pk_fma_f32 v[134:135], v[134:135], v[54:55], v[138:139]
	v_pk_fma_f32 v[132:133], v[132:133], v[52:53], v[136:137]
	global_store_dwordx4 v[152:153], v[132:135], off offset:128
	global_load_dwordx4 v[132:135], v[152:153], off offset:192 sc1
	s_waitcnt vmcnt(0)
	v_pk_fma_f32 v[130:131], v[130:131], v[6:7], v[134:135]
	v_pk_fma_f32 v[128:129], v[128:129], v[4:5], v[132:133]
	global_store_dwordx4 v[152:153], v[128:131], off offset:192
	s_nop 1
	v_or_b32_e32 v128, 16, v146
	v_ashrrev_i32_e32 v129, 31, v128
	v_lshlrev_b64 v[128:129], 12, v[128:129]
	v_lshl_add_u64 v[132:133], v[144:145], 0, v[128:129]
	global_load_dwordx4 v[128:131], v[132:133], off sc1
	s_waitcnt vmcnt(0)
	v_pk_fma_f32 v[126:127], v[126:127], v[70:71], v[130:131]
	v_pk_fma_f32 v[124:125], v[124:125], v[68:69], v[128:129]
	global_store_dwordx4 v[132:133], v[124:127], off
	global_load_dwordx4 v[124:127], v[132:133], off offset:64 sc1
	s_waitcnt vmcnt(0)
	v_pk_fma_f32 v[122:123], v[122:123], v[62:63], v[126:127]
	v_pk_fma_f32 v[120:121], v[120:121], v[60:61], v[124:125]
	global_store_dwordx4 v[132:133], v[120:123], off offset:64
	global_load_dwordx4 v[120:123], v[132:133], off offset:128 sc1
	s_waitcnt vmcnt(0)
	v_pk_fma_f32 v[118:119], v[118:119], v[54:55], v[122:123]
	v_pk_fma_f32 v[116:117], v[116:117], v[52:53], v[120:121]
	global_store_dwordx4 v[132:133], v[116:119], off offset:128
	global_load_dwordx4 v[116:119], v[132:133], off offset:192 sc1
	s_waitcnt vmcnt(0)
	v_pk_fma_f32 v[114:115], v[114:115], v[6:7], v[118:119]
	v_pk_fma_f32 v[112:113], v[112:113], v[4:5], v[116:117]
	global_store_dwordx4 v[132:133], v[112:115], off offset:192
	s_nop 1
	v_or_b32_e32 v112, 32, v146
	v_ashrrev_i32_e32 v113, 31, v112
	v_lshlrev_b64 v[112:113], 12, v[112:113]
	v_lshl_add_u64 v[116:117], v[144:145], 0, v[112:113]
	global_load_dwordx4 v[112:115], v[116:117], off sc1
	s_waitcnt vmcnt(0)
	v_pk_fma_f32 v[110:111], v[110:111], v[70:71], v[114:115]
	v_pk_fma_f32 v[108:109], v[108:109], v[68:69], v[112:113]
	global_store_dwordx4 v[116:117], v[108:111], off
	global_load_dwordx4 v[108:111], v[116:117], off offset:64 sc1
	s_waitcnt vmcnt(0)
	v_pk_fma_f32 v[106:107], v[106:107], v[62:63], v[110:111]
	v_pk_fma_f32 v[104:105], v[104:105], v[60:61], v[108:109]
	global_store_dwordx4 v[116:117], v[104:107], off offset:64
	global_load_dwordx4 v[104:107], v[116:117], off offset:128 sc1
	s_waitcnt vmcnt(0)
	v_pk_fma_f32 v[102:103], v[102:103], v[54:55], v[106:107]
	v_pk_fma_f32 v[100:101], v[100:101], v[52:53], v[104:105]
	global_store_dwordx4 v[116:117], v[100:103], off offset:128
	global_load_dwordx4 v[100:103], v[116:117], off offset:192 sc1
	s_waitcnt vmcnt(0)
	v_pk_fma_f32 v[98:99], v[98:99], v[6:7], v[102:103]
	v_pk_fma_f32 v[96:97], v[96:97], v[4:5], v[100:101]
	global_store_dwordx4 v[116:117], v[96:99], off offset:192
	s_nop 1
	v_or_b32_e32 v96, 48, v146
	v_ashrrev_i32_e32 v97, 31, v96
	v_lshlrev_b64 v[96:97], 12, v[96:97]
	v_lshl_add_u64 v[100:101], v[144:145], 0, v[96:97]
	global_load_dwordx4 v[96:99], v[100:101], off sc1
	s_waitcnt vmcnt(0)
	v_pk_fma_f32 v[94:95], v[94:95], v[70:71], v[98:99]
	v_pk_fma_f32 v[92:93], v[92:93], v[68:69], v[96:97]
	global_store_dwordx4 v[100:101], v[92:95], off
	global_load_dwordx4 v[92:95], v[100:101], off offset:64 sc1
	s_waitcnt vmcnt(0)
	v_pk_fma_f32 v[90:91], v[90:91], v[62:63], v[94:95]
	v_pk_fma_f32 v[88:89], v[88:89], v[60:61], v[92:93]
	global_store_dwordx4 v[100:101], v[88:91], off offset:64
	global_load_dwordx4 v[88:91], v[100:101], off offset:128 sc1
	s_waitcnt vmcnt(0)
	v_pk_fma_f32 v[86:87], v[86:87], v[54:55], v[90:91]
	v_pk_fma_f32 v[84:85], v[84:85], v[52:53], v[88:89]
	global_store_dwordx4 v[100:101], v[84:87], off offset:128
	global_load_dwordx4 v[84:87], v[100:101], off offset:192 sc1
	s_waitcnt vmcnt(0)
	v_pk_fma_f32 v[82:83], v[82:83], v[6:7], v[86:87]
	v_pk_fma_f32 v[80:81], v[80:81], v[4:5], v[84:85]
	global_store_dwordx4 v[100:101], v[80:83], off offset:192
	s_nop 1
	v_or_b32_e32 v80, 64, v146
	v_ashrrev_i32_e32 v81, 31, v80
	v_lshlrev_b64 v[80:81], 12, v[80:81]
	v_lshl_add_u64 v[84:85], v[144:145], 0, v[80:81]
	global_load_dwordx4 v[80:83], v[84:85], off sc1
	s_waitcnt vmcnt(0)
	v_pk_fma_f32 v[78:79], v[78:79], v[70:71], v[82:83]
	v_pk_fma_f32 v[76:77], v[76:77], v[68:69], v[80:81]
	global_store_dwordx4 v[84:85], v[76:79], off
	global_load_dwordx4 v[76:79], v[84:85], off offset:64 sc1
	s_waitcnt vmcnt(0)
	v_pk_fma_f32 v[74:75], v[74:75], v[62:63], v[78:79]
	v_pk_fma_f32 v[72:73], v[72:73], v[60:61], v[76:77]
	global_store_dwordx4 v[84:85], v[72:75], off offset:64
	global_load_dwordx4 v[72:75], v[84:85], off offset:128 sc1
	s_waitcnt vmcnt(0)
	v_pk_fma_f32 v[66:67], v[66:67], v[54:55], v[74:75]
	v_pk_fma_f32 v[64:65], v[64:65], v[52:53], v[72:73]
	global_store_dwordx4 v[84:85], v[64:67], off offset:128
	global_load_dwordx4 v[64:67], v[84:85], off offset:192 sc1
	s_waitcnt vmcnt(0)
	v_pk_fma_f32 v[58:59], v[58:59], v[6:7], v[66:67]
	v_pk_fma_f32 v[56:57], v[56:57], v[4:5], v[64:65]
	global_store_dwordx4 v[84:85], v[56:59], off offset:192
	s_nop 1
	v_or_b32_e32 v56, 0x50, v146
	v_ashrrev_i32_e32 v57, 31, v56
	v_lshlrev_b64 v[56:57], 12, v[56:57]
	v_lshl_add_u64 v[64:65], v[144:145], 0, v[56:57]
	global_load_dwordx4 v[56:59], v[64:65], off sc1
	s_waitcnt vmcnt(0)
	v_pk_fma_f32 v[50:51], v[50:51], v[70:71], v[58:59]
	v_pk_fma_f32 v[48:49], v[48:49], v[68:69], v[56:57]
	global_store_dwordx4 v[64:65], v[48:51], off
	global_load_dwordx4 v[48:51], v[64:65], off offset:64 sc1
	s_waitcnt vmcnt(0)
	v_pk_fma_f32 v[46:47], v[46:47], v[62:63], v[50:51]
	v_pk_fma_f32 v[44:45], v[44:45], v[60:61], v[48:49]
	global_store_dwordx4 v[64:65], v[44:47], off offset:64
	global_load_dwordx4 v[44:47], v[64:65], off offset:128 sc1
	s_waitcnt vmcnt(0)
	v_pk_fma_f32 v[42:43], v[42:43], v[54:55], v[46:47]
	v_pk_fma_f32 v[40:41], v[40:41], v[52:53], v[44:45]
	global_store_dwordx4 v[64:65], v[40:43], off offset:128
	global_load_dwordx4 v[40:43], v[64:65], off offset:192 sc1
	s_waitcnt vmcnt(0)
	v_pk_fma_f32 v[38:39], v[38:39], v[6:7], v[42:43]
	v_pk_fma_f32 v[36:37], v[36:37], v[4:5], v[40:41]
	global_store_dwordx4 v[64:65], v[36:39], off offset:192
	s_nop 1
	v_or_b32_e32 v36, 0x60, v146
	v_ashrrev_i32_e32 v37, 31, v36
	v_lshlrev_b64 v[36:37], 12, v[36:37]
	v_lshl_add_u64 v[40:41], v[144:145], 0, v[36:37]
	global_load_dwordx4 v[36:39], v[40:41], off sc1
	s_waitcnt vmcnt(0)
	v_pk_fma_f32 v[34:35], v[34:35], v[70:71], v[38:39]
	v_pk_fma_f32 v[32:33], v[32:33], v[68:69], v[36:37]
	global_store_dwordx4 v[40:41], v[32:35], off
	global_load_dwordx4 v[32:35], v[40:41], off offset:64 sc1
	s_waitcnt vmcnt(0)
	v_pk_fma_f32 v[30:31], v[30:31], v[62:63], v[34:35]
	v_pk_fma_f32 v[28:29], v[28:29], v[60:61], v[32:33]
	global_store_dwordx4 v[40:41], v[28:31], off offset:64
	global_load_dwordx4 v[28:31], v[40:41], off offset:128 sc1
	s_waitcnt vmcnt(0)
	v_pk_fma_f32 v[26:27], v[26:27], v[54:55], v[30:31]
	v_pk_fma_f32 v[24:25], v[24:25], v[52:53], v[28:29]
	global_store_dwordx4 v[40:41], v[24:27], off offset:128
	global_load_dwordx4 v[24:27], v[40:41], off offset:192 sc1
	s_waitcnt vmcnt(0)
	v_pk_fma_f32 v[22:23], v[22:23], v[6:7], v[26:27]
	v_pk_fma_f32 v[20:21], v[20:21], v[4:5], v[24:25]
	global_store_dwordx4 v[40:41], v[20:23], off offset:192
	s_nop 1
	v_or_b32_e32 v20, 0x70, v146
	v_ashrrev_i32_e32 v21, 31, v20
	v_lshlrev_b64 v[20:21], 12, v[20:21]
	v_lshl_add_u64 v[20:21], v[144:145], 0, v[20:21]
	global_load_dwordx4 v[22:25], v[20:21], off sc1
	s_waitcnt vmcnt(0)
	v_pk_fma_f32 v[18:19], v[18:19], v[70:71], v[24:25]
	v_pk_fma_f32 v[16:17], v[16:17], v[68:69], v[22:23]
	global_store_dwordx4 v[20:21], v[16:19], off
	global_load_dwordx4 v[16:19], v[20:21], off offset:64 sc1
	s_waitcnt vmcnt(0)
	v_pk_fma_f32 v[14:15], v[14:15], v[62:63], v[18:19]
	v_pk_fma_f32 v[12:13], v[12:13], v[60:61], v[16:17]
	global_store_dwordx4 v[20:21], v[12:15], off offset:64
	global_load_dwordx4 v[12:15], v[20:21], off offset:128 sc1
	s_waitcnt vmcnt(0)
	v_pk_fma_f32 v[10:11], v[10:11], v[54:55], v[14:15]
	v_pk_fma_f32 v[8:9], v[8:9], v[52:53], v[12:13]
	global_store_dwordx4 v[20:21], v[8:11], off offset:128
	global_load_dwordx4 v[8:11], v[20:21], off offset:192 sc1
	s_waitcnt vmcnt(0)
	v_pk_fma_f32 v[2:3], v[2:3], v[6:7], v[10:11]
	v_pk_fma_f32 v[0:1], v[0:1], v[4:5], v[8:9]
	global_store_dwordx4 v[20:21], v[0:3], off offset:192
	s_cbranch_scc0 .LBB0_909
